# v11glaEpi
# speedup vs baseline: 1.0076x; 1.0076x over previous
; #define SFLOAD(F_, dvb_) do { _Pragma("unroll") for (int ks = 0; ks < 8; ++ks) F_[ks] = *(const bf16x8*)(sp + (size_t)(dvb_) * 32 * 128 + ks * 16); } while (0)
; #define SFMMA(F_, dvb_) do { _Pragma("unroll") for (int ks = 0; ks < 8; ++ks) o[dvb_] = __builtin_amdgcn_mfma_f32_32x32x16_bf16(F_[ks], qf[ks], o[dvb_], 0, 0, 0); } while (0)
; __device__ __forceinline__ void gla_out(const Params& p, LAS unsigned char* lds, int l) {
;     ...
;             { const bf16_t* qp = proj + (size_t)(tok0 + 32 * ib + r32) * NP + C_QC + h * 128 + hi * 8;
; #pragma unroll
;               for (int ks = 0; ks < 8; ++ks) qf[ks] = *(const bf16x8*)(qp + ks * 16); }
;             { bf16x8 sfA[8];
;     ...
; #pragma unroll
;               for (int d2 = 0; d2 < 8; ++d2) { SFLOAD(sfA, d2); SFMMA(sfA, d2); asm volatile("" ::: "memory"); }
.LBB0_342:
	s_or_b64 exec, exec, s[12:13]
	s_ashr_i32 s35, s34, 31
	s_lshl_b64 s[0:1], s[34:35], 18
	v_lshl_add_u64 v[178:179], v[168:169], 0, s[0:1]
	global_load_dwordx4 v[130:133], v[158:159], off
	global_load_dwordx4 v[134:137], v[158:159], off offset:32
	global_load_dwordx4 v[138:141], v[158:159], off offset:64
	global_load_dwordx4 v[142:145], v[158:159], off offset:96
	global_load_dwordx4 v[146:149], v[158:159], off offset:128
	global_load_dwordx4 v[150:153], v[158:159], off offset:160
	global_load_dwordx4 v[154:157], v[158:159], off offset:192
	s_nop 0
	global_load_dwordx4 v[158:161], v[158:159], off offset:224
	s_nop 0
	global_load_dwordx4 v[184:187], v[178:179], off
	global_load_dwordx4 v[188:191], v[178:179], off offset:32
	global_load_dwordx4 v[192:195], v[178:179], off offset:64
	global_load_dwordx4 v[200:203], v[178:179], off offset:96
	global_load_dwordx4 v[204:207], v[178:179], off offset:128
	global_load_dwordx4 v[208:211], v[178:179], off offset:160
	global_load_dwordx4 v[212:215], v[178:179], off offset:192
	global_load_dwordx4 v[218:221], v[178:179], off offset:224
	v_add_co_u32_e32 v196, vcc, s33, v178
	s_movk_i32 s0, 0x4000
	s_nop 0
	v_addc_co_u32_e32 v197, vcc, 0, v179, vcc
	v_mov_b32_e32 v175, v1
	s_waitcnt vmcnt(7)
	v_mfma_f32_32x32x16_bf16 v[114:129], v[184:187], v[130:133], v[114:129]
	global_load_dwordx4 v[184:187], v[196:197], off
	s_waitcnt vmcnt(7)
	v_mfma_f32_32x32x16_bf16 v[114:129], v[188:191], v[134:137], v[114:129]
	global_load_dwordx4 v[188:191], v[196:197], off offset:32
	s_waitcnt vmcnt(7)
	v_mfma_f32_32x32x16_bf16 v[114:129], v[192:195], v[138:141], v[114:129]
	global_load_dwordx4 v[192:195], v[196:197], off offset:64
	s_waitcnt vmcnt(7)
	v_mfma_f32_32x32x16_bf16 v[114:129], v[200:203], v[142:145], v[114:129]
	global_load_dwordx4 v[200:203], v[196:197], off offset:96
	s_waitcnt vmcnt(7)
	v_mfma_f32_32x32x16_bf16 v[114:129], v[204:207], v[146:149], v[114:129]
	global_load_dwordx4 v[204:207], v[196:197], off offset:128
	s_waitcnt vmcnt(7)
	v_mfma_f32_32x32x16_bf16 v[114:129], v[208:211], v[150:153], v[114:129]
	global_load_dwordx4 v[208:211], v[196:197], off offset:160
	s_waitcnt vmcnt(7)
	v_mfma_f32_32x32x16_bf16 v[114:129], v[212:215], v[154:157], v[114:129]
	global_load_dwordx4 v[212:215], v[196:197], off offset:192
	s_waitcnt vmcnt(7)
	v_mfma_f32_32x32x16_bf16 v[114:129], v[218:221], v[158:161], v[114:129]
	global_load_dwordx4 v[218:221], v[196:197], off offset:224
	v_add_co_u32_e32 v196, vcc, s0, v178
	s_movk_i32 s0, 0x6000
	s_nop 0
	v_addc_co_u32_e32 v197, vcc, 0, v179, vcc
	s_waitcnt vmcnt(7)
	v_mfma_f32_32x32x16_bf16 v[98:113], v[184:187], v[130:133], v[98:113]
	global_load_dwordx4 v[184:187], v[196:197], off
	s_waitcnt vmcnt(7)
	v_mfma_f32_32x32x16_bf16 v[98:113], v[188:191], v[134:137], v[98:113]
	global_load_dwordx4 v[188:191], v[196:197], off offset:32
	s_waitcnt vmcnt(7)
	v_mfma_f32_32x32x16_bf16 v[98:113], v[192:195], v[138:141], v[98:113]
	global_load_dwordx4 v[192:195], v[196:197], off offset:64
	s_waitcnt vmcnt(7)
	v_mfma_f32_32x32x16_bf16 v[98:113], v[200:203], v[142:145], v[98:113]
	global_load_dwordx4 v[200:203], v[196:197], off offset:96
	s_waitcnt vmcnt(7)
	v_mfma_f32_32x32x16_bf16 v[98:113], v[204:207], v[146:149], v[98:113]
	global_load_dwordx4 v[204:207], v[196:197], off offset:128
	s_waitcnt vmcnt(7)
	v_mfma_f32_32x32x16_bf16 v[98:113], v[208:211], v[150:153], v[98:113]
	global_load_dwordx4 v[208:211], v[196:197], off offset:160
	s_waitcnt vmcnt(7)
	v_mfma_f32_32x32x16_bf16 v[98:113], v[212:215], v[154:157], v[98:113]
	global_load_dwordx4 v[212:215], v[196:197], off offset:192
	s_waitcnt vmcnt(7)
	v_mfma_f32_32x32x16_bf16 v[98:113], v[218:221], v[158:161], v[98:113]
	global_load_dwordx4 v[218:221], v[196:197], off offset:224
	v_add_co_u32_e32 v196, vcc, s0, v178
	s_mov_b32 s0, 0x8000
	s_nop 0
	v_addc_co_u32_e32 v197, vcc, 0, v179, vcc
	s_waitcnt vmcnt(7)
	v_mfma_f32_32x32x16_bf16 v[82:97], v[184:187], v[130:133], v[82:97]
	global_load_dwordx4 v[184:187], v[196:197], off
	s_waitcnt vmcnt(7)
	v_mfma_f32_32x32x16_bf16 v[82:97], v[188:191], v[134:137], v[82:97]
	global_load_dwordx4 v[188:191], v[196:197], off offset:32
	s_waitcnt vmcnt(7)
	v_mfma_f32_32x32x16_bf16 v[82:97], v[192:195], v[138:141], v[82:97]
	global_load_dwordx4 v[192:195], v[196:197], off offset:64
	s_waitcnt vmcnt(7)
	v_mfma_f32_32x32x16_bf16 v[82:97], v[200:203], v[142:145], v[82:97]
	global_load_dwordx4 v[200:203], v[196:197], off offset:96
	s_waitcnt vmcnt(7)
	v_mfma_f32_32x32x16_bf16 v[82:97], v[204:207], v[146:149], v[82:97]
	global_load_dwordx4 v[204:207], v[196:197], off offset:128
	s_waitcnt vmcnt(7)
	v_mfma_f32_32x32x16_bf16 v[82:97], v[208:211], v[150:153], v[82:97]
	global_load_dwordx4 v[208:211], v[196:197], off offset:160
	s_waitcnt vmcnt(7)
	v_mfma_f32_32x32x16_bf16 v[82:97], v[212:215], v[154:157], v[82:97]
	global_load_dwordx4 v[212:215], v[196:197], off offset:192
	s_waitcnt vmcnt(7)
	v_mfma_f32_32x32x16_bf16 v[82:97], v[218:221], v[158:161], v[82:97]
	global_load_dwordx4 v[218:221], v[196:197], off offset:224
	v_add_co_u32_e32 v196, vcc, s0, v178
	s_mov_b32 s0, 0xa000
	s_nop 0
	v_addc_co_u32_e32 v197, vcc, 0, v179, vcc
	s_waitcnt vmcnt(7)
	v_mfma_f32_32x32x16_bf16 v[66:81], v[184:187], v[130:133], v[66:81]
	global_load_dwordx4 v[184:187], v[196:197], off
	s_waitcnt vmcnt(7)
	v_mfma_f32_32x32x16_bf16 v[66:81], v[188:191], v[134:137], v[66:81]
	global_load_dwordx4 v[188:191], v[196:197], off offset:32
	s_waitcnt vmcnt(7)
	v_mfma_f32_32x32x16_bf16 v[66:81], v[192:195], v[138:141], v[66:81]
	global_load_dwordx4 v[192:195], v[196:197], off offset:64
	s_waitcnt vmcnt(7)
; #define SFLOAD(F_, dvb_) do { _Pragma("unroll") for (int ks = 0; ks < 8; ++ks) F_[ks] = *(const bf16x8*)(sp + (size_t)(dvb_) * 32 * 128 + ks * 16); } while (0)
; #define SFMMA(F_, dvb_) do { _Pragma("unroll") for (int ks = 0; ks < 8; ++ks) o[dvb_] = __builtin_amdgcn_mfma_f32_32x32x16_bf16(F_[ks], qf[ks], o[dvb_], 0, 0, 0); } while (0)
; __device__ __forceinline__ void gla_out(const Params& p, LAS unsigned char* lds, int l) {
;     ...
;             { const bf16_t* qp = proj + (size_t)(tok0 + 32 * ib + r32) * NP + C_QC + h * 128 + hi * 8;
; #pragma unroll
;               for (int ks = 0; ks < 8; ++ks) qf[ks] = *(const bf16x8*)(qp + ks * 16); }
;             { bf16x8 sfA[8];
;     ...
; #pragma unroll
;               for (int d2 = 0; d2 < 8; ++d2) { SFLOAD(sfA, d2); SFMMA(sfA, d2); asm volatile("" ::: "memory"); }
	v_mfma_f32_32x32x16_bf16 v[66:81], v[200:203], v[142:145], v[66:81]
	global_load_dwordx4 v[200:203], v[196:197], off offset:96
	s_waitcnt vmcnt(7)
	v_mfma_f32_32x32x16_bf16 v[66:81], v[204:207], v[146:149], v[66:81]
	global_load_dwordx4 v[204:207], v[196:197], off offset:128
	s_waitcnt vmcnt(7)
	v_mfma_f32_32x32x16_bf16 v[66:81], v[208:211], v[150:153], v[66:81]
	global_load_dwordx4 v[208:211], v[196:197], off offset:160
	s_waitcnt vmcnt(7)
	v_mfma_f32_32x32x16_bf16 v[66:81], v[212:215], v[154:157], v[66:81]
	global_load_dwordx4 v[212:215], v[196:197], off offset:192
	s_waitcnt vmcnt(7)
	v_mfma_f32_32x32x16_bf16 v[66:81], v[218:221], v[158:161], v[66:81]
	global_load_dwordx4 v[218:221], v[196:197], off offset:224
	v_add_co_u32_e32 v196, vcc, s0, v178
	s_mov_b32 s0, 0xc000
	s_nop 0
	v_addc_co_u32_e32 v197, vcc, 0, v179, vcc
	s_waitcnt vmcnt(7)
	v_mfma_f32_32x32x16_bf16 v[50:65], v[184:187], v[130:133], v[50:65]
	global_load_dwordx4 v[184:187], v[196:197], off
	s_waitcnt vmcnt(7)
	v_mfma_f32_32x32x16_bf16 v[50:65], v[188:191], v[134:137], v[50:65]
	global_load_dwordx4 v[188:191], v[196:197], off offset:32
	s_waitcnt vmcnt(7)
	v_mfma_f32_32x32x16_bf16 v[50:65], v[192:195], v[138:141], v[50:65]
	global_load_dwordx4 v[192:195], v[196:197], off offset:64
	s_waitcnt vmcnt(7)
	v_mfma_f32_32x32x16_bf16 v[50:65], v[200:203], v[142:145], v[50:65]
	global_load_dwordx4 v[200:203], v[196:197], off offset:96
	s_waitcnt vmcnt(7)
	v_mfma_f32_32x32x16_bf16 v[50:65], v[204:207], v[146:149], v[50:65]
	global_load_dwordx4 v[204:207], v[196:197], off offset:128
	s_waitcnt vmcnt(7)
	v_mfma_f32_32x32x16_bf16 v[50:65], v[208:211], v[150:153], v[50:65]
	global_load_dwordx4 v[208:211], v[196:197], off offset:160
	s_waitcnt vmcnt(7)
	v_mfma_f32_32x32x16_bf16 v[50:65], v[212:215], v[154:157], v[50:65]
	global_load_dwordx4 v[212:215], v[196:197], off offset:192
	s_waitcnt vmcnt(7)
	v_mfma_f32_32x32x16_bf16 v[50:65], v[218:221], v[158:161], v[50:65]
	global_load_dwordx4 v[218:221], v[196:197], off offset:224
	v_add_co_u32_e32 v196, vcc, s0, v178
	s_mov_b32 s0, 0xe000
	s_nop 0
	v_addc_co_u32_e32 v197, vcc, 0, v179, vcc
	v_add_co_u32_e32 v178, vcc, s0, v178
	s_mov_b64 s[0:1], 0x30a0
	s_nop 0
	v_addc_co_u32_e32 v179, vcc, 0, v179, vcc
	s_waitcnt vmcnt(7)
	v_mfma_f32_32x32x16_bf16 v[34:49], v[184:187], v[130:133], v[34:49]
	global_load_dwordx4 v[184:187], v[196:197], off
	s_waitcnt vmcnt(7)
	v_mfma_f32_32x32x16_bf16 v[34:49], v[188:191], v[134:137], v[34:49]
	global_load_dwordx4 v[188:191], v[196:197], off offset:32
	s_waitcnt vmcnt(7)
	v_mfma_f32_32x32x16_bf16 v[34:49], v[192:195], v[138:141], v[34:49]
	global_load_dwordx4 v[192:195], v[196:197], off offset:64
	s_waitcnt vmcnt(7)
	v_mfma_f32_32x32x16_bf16 v[34:49], v[200:203], v[142:145], v[34:49]
	global_load_dwordx4 v[200:203], v[196:197], off offset:96
	s_waitcnt vmcnt(7)
	v_mfma_f32_32x32x16_bf16 v[34:49], v[204:207], v[146:149], v[34:49]
	global_load_dwordx4 v[204:207], v[196:197], off offset:128
	s_waitcnt vmcnt(7)
	v_mfma_f32_32x32x16_bf16 v[34:49], v[208:211], v[150:153], v[34:49]
	global_load_dwordx4 v[208:211], v[196:197], off offset:160
	s_waitcnt vmcnt(7)
	v_mfma_f32_32x32x16_bf16 v[34:49], v[212:215], v[154:157], v[34:49]
	global_load_dwordx4 v[212:215], v[196:197], off offset:192
	s_waitcnt vmcnt(7)
	v_mfma_f32_32x32x16_bf16 v[34:49], v[218:221], v[158:161], v[34:49]
	global_load_dwordx4 v[218:221], v[196:197], off offset:224
	s_waitcnt vmcnt(7)
	v_mfma_f32_32x32x16_bf16 v[18:33], v[184:187], v[130:133], v[18:33]
	s_waitcnt vmcnt(6)
	v_mfma_f32_32x32x16_bf16 v[18:33], v[188:191], v[134:137], v[18:33]
	s_waitcnt vmcnt(5)
	v_mfma_f32_32x32x16_bf16 v[18:33], v[192:195], v[138:141], v[18:33]
	s_waitcnt vmcnt(4)
	v_mfma_f32_32x32x16_bf16 v[18:33], v[200:203], v[142:145], v[18:33]
	s_waitcnt vmcnt(3)
	v_mfma_f32_32x32x16_bf16 v[18:33], v[204:207], v[146:149], v[18:33]
	s_waitcnt vmcnt(2)
	v_mfma_f32_32x32x16_bf16 v[18:33], v[208:211], v[150:153], v[18:33]
	s_waitcnt vmcnt(1)
	v_mfma_f32_32x32x16_bf16 v[18:33], v[212:215], v[154:157], v[18:33]
	s_waitcnt vmcnt(0)
	v_mfma_f32_32x32x16_bf16 v[18:33], v[218:221], v[158:161], v[18:33]
	global_load_dwordx4 v[184:187], v[178:179], off
	global_load_dwordx4 v[188:191], v[178:179], off offset:32
	global_load_dwordx4 v[192:195], v[178:179], off offset:64
	global_load_dwordx4 v[200:203], v[178:179], off offset:96
	global_load_dwordx4 v[204:207], v[178:179], off offset:128
	global_load_dwordx4 v[208:211], v[178:179], off offset:160
	global_load_dwordx4 v[212:215], v[178:179], off offset:192
	global_load_dwordx4 v[218:221], v[178:179], off offset:224
	s_waitcnt vmcnt(7)
	v_mfma_f32_32x32x16_bf16 v[2:17], v[184:187], v[130:133], v[2:17]
	s_waitcnt vmcnt(6)
	v_mfma_f32_32x32x16_bf16 v[2:17], v[188:191], v[134:137], v[2:17]
	s_waitcnt vmcnt(5)
; #define SFLOAD(F_, dvb_) do { _Pragma("unroll") for (int ks = 0; ks < 8; ++ks) F_[ks] = *(const bf16x8*)(sp + (size_t)(dvb_) * 32 * 128 + ks * 16); } while (0)
; #define SFMMA(F_, dvb_) do { _Pragma("unroll") for (int ks = 0; ks < 8; ++ks) o[dvb_] = __builtin_amdgcn_mfma_f32_32x32x16_bf16(F_[ks], qf[ks], o[dvb_], 0, 0, 0); } while (0)
; __device__ __forceinline__ void gla_out(const Params& p, LAS unsigned char* lds, int l) {
;     ...
;               for (int d2 = 0; d2 < 8; ++d2) { SFLOAD(sfA, d2); SFMMA(sfA, d2); asm volatile("" ::: "memory"); }
;     ...
;             }
;             float ss = 0.f;
; #pragma unroll
;             for (int dvb = 0; dvb < 8; ++dvb)
; #pragma unroll
;                 for (int r = 0; r < 16; ++r) ss += o[dvb][r] * o[dvb][r];
;             ss += __shfl_xor(ss, 32);
;             const float rs = rsqrtf(ss * (1.f / 256.f) + EPS);
	v_mfma_f32_32x32x16_bf16 v[2:17], v[192:195], v[138:141], v[2:17]
	v_mul_f32_e32 v140, v115, v115
	v_fmac_f32_e32 v140, v114, v114
	v_fmac_f32_e32 v140, v116, v116
	v_fmac_f32_e32 v140, v117, v117
	v_fmac_f32_e32 v140, v118, v118
	v_fmac_f32_e32 v140, v119, v119
	v_fmac_f32_e32 v140, v120, v120
	v_fmac_f32_e32 v140, v121, v121
	v_fmac_f32_e32 v140, v122, v122
	v_fmac_f32_e32 v140, v123, v123
	v_fmac_f32_e32 v140, v124, v124
	v_fmac_f32_e32 v140, v125, v125
	v_fmac_f32_e32 v140, v126, v126
	v_fmac_f32_e32 v140, v127, v127
	v_fmac_f32_e32 v140, v128, v128
	v_fmac_f32_e32 v140, v129, v129
	v_fmac_f32_e32 v140, v98, v98
	v_fmac_f32_e32 v140, v99, v99
	v_fmac_f32_e32 v140, v100, v100
	v_fmac_f32_e32 v140, v101, v101
	v_fmac_f32_e32 v140, v102, v102
	v_fmac_f32_e32 v140, v103, v103
	v_fmac_f32_e32 v140, v104, v104
	v_fmac_f32_e32 v140, v105, v105
	v_fmac_f32_e32 v140, v106, v106
	v_fmac_f32_e32 v140, v107, v107
	v_fmac_f32_e32 v140, v108, v108
	v_fmac_f32_e32 v140, v109, v109
	v_fmac_f32_e32 v140, v110, v110
	v_fmac_f32_e32 v140, v111, v111
	v_fmac_f32_e32 v140, v112, v112
	v_fmac_f32_e32 v140, v113, v113
	v_fmac_f32_e32 v140, v82, v82
	v_fmac_f32_e32 v140, v83, v83
	v_fmac_f32_e32 v140, v84, v84
	v_fmac_f32_e32 v140, v85, v85
	v_fmac_f32_e32 v140, v86, v86
	v_fmac_f32_e32 v140, v87, v87
	v_fmac_f32_e32 v140, v88, v88
	v_fmac_f32_e32 v140, v89, v89
	v_fmac_f32_e32 v140, v90, v90
	v_fmac_f32_e32 v140, v91, v91
	v_fmac_f32_e32 v140, v92, v92
	v_fmac_f32_e32 v140, v93, v93
	v_fmac_f32_e32 v140, v94, v94
	v_fmac_f32_e32 v140, v95, v95
	v_fmac_f32_e32 v140, v96, v96
	v_fmac_f32_e32 v140, v97, v97
	v_fmac_f32_e32 v140, v66, v66
	v_fmac_f32_e32 v140, v67, v67
	v_fmac_f32_e32 v140, v68, v68
	v_fmac_f32_e32 v140, v69, v69
	v_fmac_f32_e32 v140, v70, v70
	v_fmac_f32_e32 v140, v71, v71
	v_fmac_f32_e32 v140, v72, v72
	v_fmac_f32_e32 v140, v73, v73
	v_fmac_f32_e32 v140, v74, v74
	v_fmac_f32_e32 v140, v75, v75
	v_fmac_f32_e32 v140, v76, v76
	v_fmac_f32_e32 v140, v77, v77
	v_fmac_f32_e32 v140, v78, v78
	v_fmac_f32_e32 v140, v79, v79
	v_fmac_f32_e32 v140, v80, v80
	v_fmac_f32_e32 v140, v81, v81
	v_fmac_f32_e32 v140, v50, v50
	v_fmac_f32_e32 v140, v51, v51
	v_fmac_f32_e32 v140, v52, v52
	v_fmac_f32_e32 v140, v53, v53
	v_fmac_f32_e32 v140, v54, v54
	v_fmac_f32_e32 v140, v55, v55
	v_fmac_f32_e32 v140, v56, v56
	v_fmac_f32_e32 v140, v57, v57
	s_waitcnt vmcnt(4)
	v_mfma_f32_32x32x16_bf16 v[2:17], v[200:203], v[142:145], v[2:17]
	v_fmac_f32_e32 v140, v58, v58
	v_fmac_f32_e32 v140, v59, v59
	v_fmac_f32_e32 v140, v60, v60
	v_fmac_f32_e32 v140, v61, v61
	v_fmac_f32_e32 v140, v62, v62
	v_fmac_f32_e32 v140, v63, v63
	v_fmac_f32_e32 v140, v64, v64
	v_fmac_f32_e32 v140, v65, v65
	s_waitcnt vmcnt(3)
	v_mfma_f32_32x32x16_bf16 v[2:17], v[204:207], v[146:149], v[2:17]
	v_fmac_f32_e32 v140, v34, v34
	v_fmac_f32_e32 v140, v35, v35
	v_fmac_f32_e32 v140, v36, v36
	v_fmac_f32_e32 v140, v37, v37
	v_fmac_f32_e32 v140, v38, v38
	v_fmac_f32_e32 v140, v39, v39
	v_fmac_f32_e32 v140, v40, v40
	v_fmac_f32_e32 v140, v41, v41
	s_waitcnt vmcnt(2)
	v_mfma_f32_32x32x16_bf16 v[2:17], v[208:211], v[150:153], v[2:17]
	v_fmac_f32_e32 v140, v42, v42
	v_fmac_f32_e32 v140, v43, v43
	v_fmac_f32_e32 v140, v44, v44
	v_fmac_f32_e32 v140, v45, v45
	v_fmac_f32_e32 v140, v46, v46
	v_fmac_f32_e32 v140, v47, v47
	v_fmac_f32_e32 v140, v48, v48
	v_fmac_f32_e32 v140, v49, v49
	s_waitcnt vmcnt(1)
	v_mfma_f32_32x32x16_bf16 v[2:17], v[212:215], v[154:157], v[2:17]
	v_fmac_f32_e32 v140, v18, v18
	v_fmac_f32_e32 v140, v19, v19
	v_fmac_f32_e32 v140, v20, v20
	v_fmac_f32_e32 v140, v21, v21
	v_fmac_f32_e32 v140, v22, v22
	v_fmac_f32_e32 v140, v23, v23
	v_fmac_f32_e32 v140, v24, v24
	v_fmac_f32_e32 v140, v25, v25
	s_waitcnt vmcnt(0)
	v_mfma_f32_32x32x16_bf16 v[2:17], v[218:221], v[158:161], v[2:17]
	v_fmac_f32_e32 v140, v26, v26
	v_fmac_f32_e32 v140, v27, v27
	v_fmac_f32_e32 v140, v28, v28
	v_fmac_f32_e32 v140, v29, v29
	v_fmac_f32_e32 v140, v30, v30
	v_fmac_f32_e32 v140, v31, v31
	v_fmac_f32_e32 v140, v32, v32
	v_fmac_f32_e32 v140, v33, v33
	s_nop 3
	v_fmac_f32_e32 v140, v2, v2
	v_fmac_f32_e32 v140, v3, v3
	v_fmac_f32_e32 v140, v4, v4
	v_fmac_f32_e32 v140, v5, v5
	v_fmac_f32_e32 v140, v6, v6
	v_fmac_f32_e32 v140, v7, v7
	v_pk_mul_f32 v[138:139], v[8:9], v[8:9]
	v_pk_mul_f32 v[136:137], v[10:11], v[10:11]
	v_add_f32_e32 v138, v138, v140
	v_add_f32_e32 v138, v139, v138
	v_add_f32_e32 v136, v136, v138
	v_pk_mul_f32 v[134:135], v[12:13], v[12:13]
	v_add_f32_e32 v136, v137, v136
	v_add_f32_e32 v134, v134, v136
	v_pk_mul_f32 v[132:133], v[14:15], v[14:15]
	v_add_f32_e32 v134, v135, v134
	v_add_f32_e32 v132, v132, v134
	v_pk_mul_f32 v[130:131], v[16:17], v[16:17]
	v_add_f32_e32 v132, v133, v132
	v_add_f32_e32 v130, v130, v132
	v_and_b32_e32 v132, 64, v252
	v_add_f32_e32 v130, v131, v130
	v_xor_b32_e32 v131, 32, v252
	v_add_u32_e32 v132, 64, v132
	v_cmp_lt_i32_e32 vcc, v131, v132
	s_nop 1
	v_cndmask_b32_e32 v131, v252, v131, vcc
	v_lshlrev_b32_e32 v131, 2, v131
	ds_bpermute_b32 v131, v131, v130
	s_waitcnt lgkmcnt(0)
; __device__ __forceinline__ unsigned cvt_pk_bf16(float lo, float hi) { unsigned r; asm volatile("v_cvt_pk_bf16_f32 %0, %1, %2" : "=v"(r) : "v"(lo), "v"(hi)); return r; }
; __device__ __forceinline__ float bf_lo(unsigned w) { return __uint_as_float(w << 16); }
; __device__ __forceinline__ float bf_hi(unsigned w) { return __uint_as_float(w & 0xffff0000u); }
; __device__ __forceinline__ float siluf_(float v) { return v * sigmoidf_(v); }
; __device__ __forceinline__ void gla_out(const Params& p, LAS unsigned char* lds, int l) {
;     ...
;             ss += __shfl_xor(ss, 32);
;             const float rs = rsqrtf(ss * (1.f / 256.f) + EPS);
;             bf16_t* zp = proj + (size_t)(tok0 + 32 * ib + r32) * NP + C_ZC + h * 256; const float* gn = p.gla_norm + l * 1024 + h * 256;
; #pragma unroll
;             for (int dvb = 0; dvb < 8; ++dvb)
; #pragma unroll
;                 for (int rq = 0; rq < 4; ++rq) { const int dv = dvb * 32 + 8 * rq + 4 * hi; const u32x2 zz = *(const u32x2*)(zp + dv); const f32x4 g4 = *(const f32x4*)(gn + dv);
;                     const float y0 = o[dvb][rq * 4 + 0] * rs * g4[0] * siluf_(bf_lo(zz.x)), y1 = o[dvb][rq * 4 + 1] * rs * g4[1] * siluf_(bf_hi(zz.x));
;                     const float y2 = o[dvb][rq * 4 + 2] * rs * g4[2] * siluf_(bf_lo(zz.y)), y3 = o[dvb][rq * 4 + 3] * rs * g4[3] * siluf_(bf_hi(zz.y));
;                     u32x2 w; w.x = cvt_pk_bf16(y0, y1); w.y = cvt_pk_bf16(y2, y3); *(u32x2*)(zp + dv) = w; }
	v_add_f32_e32 v130, v130, v131
	v_fmamk_f32 v130, v130, 0x3b800000, v198
	v_cmp_gt_f32_e32 vcc, s28, v130
	v_mul_f32_e32 v131, 0x4b800000, v130
	s_nop 0
	v_cndmask_b32_e32 v130, v130, v131, vcc
	v_rsq_f32_e32 v130, v130
	s_nop 0
	v_mul_f32_e32 v131, 0x45800000, v130
	v_cndmask_b32_e32 v140, v130, v131, vcc
	v_lshl_add_u64 v[130:131], v[164:165], 1, v[176:177]
	v_lshl_add_u64 v[130:131], v[130:131], 0, v[174:175]
	v_add_co_u32_e32 v136, vcc, s53, v130
	v_lshl_add_u64 v[134:135], v[130:131], 0, s[0:1]
	s_nop 0
	v_addc_co_u32_e32 v137, vcc, 0, v131, vcc
	v_and_b32_e32 v248, 63, v199
	v_lshrrev_b32_e32 v249, 5, v248
	v_sub_u32_e32 v248, v248, v249
	v_lshlrev_b32_e32 v248, 4, v248
	v_mov_b32_e32 v249, 0
	v_lshl_add_u64 v[242:243], v[170:171], 0, v[248:249]
	global_load_dwordx4 v[244:247], v[242:243], off
	global_load_dwordx2 v[184:185], v[134:135], off offset:0
	global_load_dwordx2 v[186:187], v[134:135], off offset:16
	global_load_dwordx2 v[188:189], v[134:135], off offset:32
	global_load_dwordx2 v[190:191], v[134:135], off offset:48
	global_load_dwordx2 v[192:193], v[134:135], off offset:64
	global_load_dwordx2 v[194:195], v[134:135], off offset:80
	global_load_dwordx2 v[200:201], v[134:135], off offset:96
	global_load_dwordx2 v[202:203], v[134:135], off offset:112
	global_load_dwordx2 v[204:205], v[134:135], off offset:128
	global_load_dwordx2 v[206:207], v[134:135], off offset:144
	global_load_dwordx2 v[208:209], v[134:135], off offset:160
	global_load_dwordx2 v[210:211], v[134:135], off offset:176
	global_load_dwordx2 v[212:213], v[134:135], off offset:192
	global_load_dwordx2 v[214:215], v[134:135], off offset:208
	global_load_dwordx2 v[218:219], v[134:135], off offset:224
	global_load_dwordx2 v[220:221], v[134:135], off offset:240
	global_load_dwordx2 v[146:147], v[134:135], off offset:256
	global_load_dwordx2 v[148:149], v[134:135], off offset:272
	global_load_dwordx2 v[150:151], v[134:135], off offset:288
	global_load_dwordx2 v[152:153], v[134:135], off offset:304
	global_load_dwordx2 v[154:155], v[134:135], off offset:320
	global_load_dwordx2 v[156:157], v[134:135], off offset:336
	global_load_dwordx2 v[158:159], v[134:135], off offset:352
	global_load_dwordx2 v[160:161], v[134:135], off offset:368
	global_load_dwordx2 v[226:227], v[134:135], off offset:384
	global_load_dwordx2 v[228:229], v[134:135], off offset:400
	global_load_dwordx2 v[230:231], v[134:135], off offset:416
	global_load_dwordx2 v[232:233], v[134:135], off offset:432
	global_load_dwordx2 v[234:235], v[134:135], off offset:448
	global_load_dwordx2 v[236:237], v[134:135], off offset:464
	global_load_dwordx2 v[238:239], v[134:135], off offset:480
	global_load_dwordx2 v[240:241], v[134:135], off offset:496
	v_lshrrev_b32_e32 v242, 7, v199
	v_lshlrev_b32_e32 v242, 10, v242
	v_add_u32_e32 v242, 0x21000, v242
	v_and_b32_e32 v243, 63, v199
	v_lshl_add_u32 v243, v243, 4, v242
	v_bfe_u32 v248, v199, 5, 1
	v_lshl_add_u32 v242, v248, 4, v242
	s_waitcnt vmcnt(32)
	ds_write_b128 v243, v[244:247]
	s_waitcnt lgkmcnt(0)
	ds_read_b128 v[130:133], v242 offset:0
	v_mul_f32_e32 v143, v114, v140
	v_mul_f32_e32 v115, v115, v140
	v_mul_f32_e32 v119, v119, v140
	s_mov_b32 s0, s96
	s_waitcnt vmcnt(31)
	v_mov_b32_e32 v138, v184
	v_mov_b32_e32 v139, v185
	v_lshlrev_b32_e32 v142, 16, v138
	v_mul_f32_e32 v114, 0xbfb8aa3b, v142
	v_exp_f32_e32 v114, v114
	s_waitcnt lgkmcnt(0)
	v_mov_b32_e32 v145, v130
	v_add_f32_e32 v114, 1.0, v114
	v_rcp_f32_e32 v144, v114
	v_and_b32_e32 v114, 0xffff0000, v138
	v_mul_f32_e32 v130, 0xbfb8aa3b, v114
	v_exp_f32_e32 v130, v130
	v_pk_mul_f32 v[142:143], v[144:145], v[142:143]
	v_add_f32_e32 v130, 1.0, v130
	v_rcp_f32_e32 v130, v130
	v_mul_f32_e32 v141, v142, v143
	v_pk_mul_f32 v[114:115], v[130:131], v[114:115]
	s_nop 0
	v_mul_f32_e32 v138, v114, v115
	v_lshlrev_b32_e32 v114, 16, v139
	v_mul_f32_e32 v115, v116, v140
	v_mul_f32_e32 v116, 0xbfb8aa3b, v114
	v_exp_f32_e32 v116, v116
	v_mov_b32_e32 v131, v132
	v_add_f32_e32 v116, 1.0, v116
	v_rcp_f32_e32 v130, v116
	s_nop 0
	v_pk_mul_f32 v[114:115], v[130:131], v[114:115]
	s_nop 0
	v_mul_f32_e32 v116, v114, v115
	v_and_b32_e32 v114, 0xffff0000, v139
	v_mul_f32_e32 v115, v117, v140
	v_mul_f32_e32 v117, 0xbfb8aa3b, v114
	v_exp_f32_e32 v117, v117
	s_nop 0
	v_add_f32_e32 v117, 1.0, v117
	v_rcp_f32_e32 v132, v117
	s_nop 0
	v_pk_mul_f32 v[114:115], v[132:133], v[114:115]
	s_nop 0
	v_mul_f32_e32 v115, v114, v115
	v_cvt_pk_bf16_f32 v114, v141, v138
	v_cvt_pk_bf16_f32 v115, v116, v115
	global_store_dwordx2 v[136:137], v[114:115], off offset:160
	s_nop 0
	ds_read_b128 v[114:117], v242 offset:32
	v_mul_f32_e32 v133, v118, v140
	s_waitcnt vmcnt(31)
	v_mov_b32_e32 v130, v186
	v_mov_b32_e32 v131, v187
	v_lshlrev_b32_e32 v132, 16, v130
	v_mul_f32_e32 v118, 0xbfb8aa3b, v132
	v_exp_f32_e32 v118, v118
	s_waitcnt lgkmcnt(0)
	v_mov_b32_e32 v137, v114
	v_add_f32_e32 v118, 1.0, v118
	v_rcp_f32_e32 v136, v118
	v_and_b32_e32 v118, 0xffff0000, v130
	v_mul_f32_e32 v114, 0xbfb8aa3b, v118
	v_exp_f32_e32 v114, v114
	v_pk_mul_f32 v[132:133], v[136:137], v[132:133]
	v_add_f32_e32 v114, 1.0, v114
	v_rcp_f32_e32 v114, v114
	v_mul_f32_e32 v132, v132, v133
	v_pk_mul_f32 v[114:115], v[114:115], v[118:119]
	s_nop 0
	v_mul_f32_e32 v130, v114, v115
	v_lshlrev_b32_e32 v114, 16, v131
	v_mul_f32_e32 v118, 0xbfb8aa3b, v114
	v_exp_f32_e32 v118, v118
	v_mul_f32_e32 v115, v120, v140
	v_mov_b32_e32 v119, v116
	v_add_f32_e32 v118, 1.0, v118
	v_rcp_f32_e32 v118, v118
	s_nop 0
	v_pk_mul_f32 v[114:115], v[118:119], v[114:115]
	s_nop 0
	v_mul_f32_e32 v118, v114, v115
	v_and_b32_e32 v114, 0xffff0000, v131
	v_mul_f32_e32 v116, 0xbfb8aa3b, v114
	v_exp_f32_e32 v116, v116
	v_mul_f32_e32 v115, v121, v140
	v_mul_f32_e32 v121, v122, v140
	v_add_f32_e32 v116, 1.0, v116
	v_rcp_f32_e32 v116, v116
	s_nop 0
	v_pk_mul_f32 v[114:115], v[116:117], v[114:115]
	s_nop 0
	v_mul_f32_e32 v115, v114, v115
	v_cvt_pk_bf16_f32 v114, v132, v130
	v_cvt_pk_bf16_f32 v115, v118, v115
	global_store_dwordx2 v[134:135], v[114:115], off offset:16
	s_nop 0
	ds_read_b128 v[114:117], v242 offset:64
	s_waitcnt vmcnt(31)
; __device__ __forceinline__ unsigned cvt_pk_bf16(float lo, float hi) { unsigned r; asm volatile("v_cvt_pk_bf16_f32 %0, %1, %2" : "=v"(r) : "v"(lo), "v"(hi)); return r; }
; __device__ __forceinline__ float bf_lo(unsigned w) { return __uint_as_float(w << 16); }
; __device__ __forceinline__ float bf_hi(unsigned w) { return __uint_as_float(w & 0xffff0000u); }
; __device__ __forceinline__ float siluf_(float v) { return v * sigmoidf_(v); }
; __device__ __forceinline__ void gla_out(const Params& p, LAS unsigned char* lds, int l) {
;     ...
;             for (int dvb = 0; dvb < 8; ++dvb)
; #pragma unroll
;                 for (int rq = 0; rq < 4; ++rq) { const int dv = dvb * 32 + 8 * rq + 4 * hi; const u32x2 zz = *(const u32x2*)(zp + dv); const f32x4 g4 = *(const f32x4*)(gn + dv);
;                     const float y0 = o[dvb][rq * 4 + 0] * rs * g4[0] * siluf_(bf_lo(zz.x)), y1 = o[dvb][rq * 4 + 1] * rs * g4[1] * siluf_(bf_hi(zz.x));
;                     const float y2 = o[dvb][rq * 4 + 2] * rs * g4[2] * siluf_(bf_lo(zz.y)), y3 = o[dvb][rq * 4 + 3] * rs * g4[3] * siluf_(bf_hi(zz.y));
;                     u32x2 w; w.x = cvt_pk_bf16(y0, y1); w.y = cvt_pk_bf16(y2, y3); *(u32x2*)(zp + dv) = w; }
	v_mov_b32_e32 v118, v188
	v_mov_b32_e32 v119, v189
	v_lshlrev_b32_e32 v120, 16, v118
	v_mul_f32_e32 v122, 0xbfb8aa3b, v120
	v_exp_f32_e32 v122, v122
	s_waitcnt lgkmcnt(0)
	v_mov_b32_e32 v131, v114
	v_add_f32_e32 v122, 1.0, v122
	v_rcp_f32_e32 v130, v122
	s_nop 0
	v_pk_mul_f32 v[120:121], v[130:131], v[120:121]
	s_nop 0
	v_mul_f32_e32 v122, v120, v121
	v_and_b32_e32 v120, 0xffff0000, v118
	v_mul_f32_e32 v114, 0xbfb8aa3b, v120
	v_exp_f32_e32 v114, v114
	v_mul_f32_e32 v121, v123, v140
	v_add_f32_e32 v114, 1.0, v114
	v_rcp_f32_e32 v114, v114
	s_nop 0
	v_pk_mul_f32 v[114:115], v[114:115], v[120:121]
	s_nop 0
	v_mul_f32_e32 v118, v114, v115
	v_lshlrev_b32_e32 v114, 16, v119
	v_mul_f32_e32 v120, 0xbfb8aa3b, v114
	v_exp_f32_e32 v120, v120
	v_mul_f32_e32 v115, v124, v140
	v_mov_b32_e32 v121, v116
	v_add_f32_e32 v120, 1.0, v120
	v_rcp_f32_e32 v120, v120
	s_nop 0
	v_pk_mul_f32 v[114:115], v[120:121], v[114:115]
	s_nop 0
	v_mul_f32_e32 v120, v114, v115
	v_and_b32_e32 v114, 0xffff0000, v119
	v_mul_f32_e32 v116, 0xbfb8aa3b, v114
	v_exp_f32_e32 v116, v116
	v_mul_f32_e32 v115, v125, v140
	v_mul_f32_e32 v121, v126, v140
	v_add_f32_e32 v116, 1.0, v116
	v_rcp_f32_e32 v116, v116
	s_nop 0
	v_pk_mul_f32 v[114:115], v[116:117], v[114:115]
	s_nop 0
	v_mul_f32_e32 v115, v114, v115
	v_cvt_pk_bf16_f32 v114, v122, v118
	v_cvt_pk_bf16_f32 v115, v120, v115
	global_store_dwordx2 v[134:135], v[114:115], off offset:32
	s_nop 0
	ds_read_b128 v[114:117], v242 offset:96
	s_waitcnt vmcnt(31)
	v_mov_b32_e32 v118, v190
	v_mov_b32_e32 v119, v191
	v_lshlrev_b32_e32 v120, 16, v118
	v_mul_f32_e32 v122, 0xbfb8aa3b, v120
	v_exp_f32_e32 v122, v122
	s_waitcnt lgkmcnt(0)
	v_mov_b32_e32 v123, v114
	v_add_f32_e32 v122, 1.0, v122
	v_rcp_f32_e32 v122, v122
	s_nop 0
	v_pk_mul_f32 v[120:121], v[122:123], v[120:121]
	s_nop 0
	v_mul_f32_e32 v122, v120, v121
	v_and_b32_e32 v120, 0xffff0000, v118
	v_mul_f32_e32 v114, 0xbfb8aa3b, v120
	v_exp_f32_e32 v114, v114
	v_mul_f32_e32 v121, v127, v140
	v_add_f32_e32 v114, 1.0, v114
	v_rcp_f32_e32 v114, v114
	s_nop 0
	v_pk_mul_f32 v[114:115], v[114:115], v[120:121]
	s_nop 0
	v_mul_f32_e32 v118, v114, v115
	v_lshlrev_b32_e32 v114, 16, v119
	v_mul_f32_e32 v120, 0xbfb8aa3b, v114
	v_exp_f32_e32 v120, v120
	v_mul_f32_e32 v115, v128, v140
	v_mov_b32_e32 v121, v116
	v_add_f32_e32 v120, 1.0, v120
	v_rcp_f32_e32 v120, v120
	s_nop 0
	v_pk_mul_f32 v[114:115], v[120:121], v[114:115]
	s_nop 0
	v_mul_f32_e32 v120, v114, v115
	v_and_b32_e32 v114, 0xffff0000, v119
	v_mul_f32_e32 v116, 0xbfb8aa3b, v114
	v_exp_f32_e32 v116, v116
	v_mul_f32_e32 v115, v129, v140
	v_add_f32_e32 v116, 1.0, v116
	v_rcp_f32_e32 v116, v116
	s_nop 0
	v_pk_mul_f32 v[114:115], v[116:117], v[114:115]
	s_nop 0
	v_mul_f32_e32 v115, v114, v115
	v_cvt_pk_bf16_f32 v114, v122, v118
	v_cvt_pk_bf16_f32 v115, v120, v115
	global_store_dwordx2 v[134:135], v[114:115], off offset:48
	s_nop 0
	ds_read_b128 v[114:117], v242 offset:128
	v_mul_f32_e32 v120, v98, v140
	s_waitcnt vmcnt(31)
	v_mov_b32_e32 v118, v192
	v_mov_b32_e32 v119, v193
	v_lshlrev_b32_e32 v121, 16, v118
	v_mul_f32_e32 v98, 0xbfb8aa3b, v121
	v_exp_f32_e32 v98, v98
	s_waitcnt lgkmcnt(0)
	v_mov_b32_e32 v122, v114
	v_add_f32_e32 v98, 1.0, v98
	v_rcp_f32_e32 v123, v98
	v_mul_f32_e32 v98, v99, v140
	v_and_b32_e32 v99, 0xffff0000, v118
	v_mul_f32_e32 v114, 0xbfb8aa3b, v99
	v_exp_f32_e32 v114, v114
	v_pk_mul_f32 v[120:121], v[122:123], v[120:121]
	v_add_f32_e32 v114, 1.0, v114
	v_mul_f32_e32 v122, v120, v121
	v_rcp_f32_e32 v121, v114
	v_mov_b32_e32 v120, v115
	v_mov_b32_e32 v114, v116
	v_mul_f32_e32 v116, v102, v140
	v_pk_mul_f32 v[98:99], v[120:121], v[98:99]
	s_nop 0
	v_mul_f32_e32 v118, v98, v99
	v_lshlrev_b32_e32 v99, 16, v119
	v_mul_f32_e32 v98, v100, v140
	v_mul_f32_e32 v100, 0xbfb8aa3b, v99
	v_exp_f32_e32 v100, v100
	s_nop 0
	v_add_f32_e32 v100, 1.0, v100
	v_rcp_f32_e32 v115, v100
	s_nop 0
	v_pk_mul_f32 v[98:99], v[114:115], v[98:99]
	s_nop 0
	v_mul_f32_e32 v114, v98, v99
	v_and_b32_e32 v99, 0xffff0000, v119
	v_mul_f32_e32 v100, 0xbfb8aa3b, v99
	v_exp_f32_e32 v100, v100
	v_mul_f32_e32 v98, v101, v140
	v_add_f32_e32 v100, 1.0, v100
	v_rcp_f32_e32 v101, v100
	v_mov_b32_e32 v100, v117
	v_pk_mul_f32 v[98:99], v[100:101], v[98:99]
	s_nop 0
	v_mul_f32_e32 v99, v98, v99
	v_cvt_pk_bf16_f32 v98, v122, v118
	v_cvt_pk_bf16_f32 v99, v114, v99
	global_store_dwordx2 v[134:135], v[98:99], off offset:64
	s_nop 0
	ds_read_b128 v[98:101], v242 offset:160
	s_waitcnt vmcnt(31)
	v_mov_b32_e32 v114, v194
	v_mov_b32_e32 v115, v195
	v_lshlrev_b32_e32 v119, 16, v114
	v_mul_f32_e32 v102, 0xbfb8aa3b, v119
	v_exp_f32_e32 v102, v102
	s_waitcnt lgkmcnt(0)
	v_mov_b32_e32 v118, v98
	v_add_f32_e32 v102, 1.0, v102
	v_rcp_f32_e32 v117, v102
	v_mul_f32_e32 v102, v103, v140
	v_pk_mul_f32 v[116:117], v[116:117], v[118:119]
	s_nop 0
	v_mul_f32_e32 v118, v116, v117
	v_and_b32_e32 v117, 0xffff0000, v114
	v_mul_f32_e32 v98, 0xbfb8aa3b, v117
	v_exp_f32_e32 v98, v98
	v_mov_b32_e32 v116, v99
	v_add_f32_e32 v98, 1.0, v98
	v_rcp_f32_e32 v103, v98
	s_nop 0
	v_pk_mul_f32 v[98:99], v[102:103], v[116:117]
	v_lshlrev_b32_e32 v103, 16, v115
	v_mul_f32_e32 v114, v98, v99
	v_mul_f32_e32 v99, 0xbfb8aa3b, v103
	v_exp_f32_e32 v99, v99
	v_mul_f32_e32 v98, v104, v140
	v_mov_b32_e32 v102, v100
	v_mul_f32_e32 v104, v106, v140
	v_add_f32_e32 v99, 1.0, v99
	v_rcp_f32_e32 v99, v99
	s_nop 0
	v_pk_mul_f32 v[98:99], v[98:99], v[102:103]
	v_and_b32_e32 v103, 0xffff0000, v115
	v_mul_f32_e32 v100, v98, v99
	v_mul_f32_e32 v99, 0xbfb8aa3b, v103
	v_exp_f32_e32 v99, v99
	v_mul_f32_e32 v98, v105, v140
	v_mov_b32_e32 v102, v101
	v_add_f32_e32 v99, 1.0, v99
	v_rcp_f32_e32 v99, v99
	s_nop 0
	v_pk_mul_f32 v[98:99], v[98:99], v[102:103]
	s_nop 0
	v_mul_f32_e32 v99, v98, v99
	v_cvt_pk_bf16_f32 v98, v118, v114
	v_cvt_pk_bf16_f32 v99, v100, v99
	global_store_dwordx2 v[134:135], v[98:99], off offset:80
	s_nop 0
	ds_read_b128 v[98:101], v242 offset:192
	s_waitcnt vmcnt(31)
; __device__ __forceinline__ unsigned cvt_pk_bf16(float lo, float hi) { unsigned r; asm volatile("v_cvt_pk_bf16_f32 %0, %1, %2" : "=v"(r) : "v"(lo), "v"(hi)); return r; }
; __device__ __forceinline__ float bf_lo(unsigned w) { return __uint_as_float(w << 16); }
; __device__ __forceinline__ float bf_hi(unsigned w) { return __uint_as_float(w & 0xffff0000u); }
; __device__ __forceinline__ float siluf_(float v) { return v * sigmoidf_(v); }
; __device__ __forceinline__ void gla_out(const Params& p, LAS unsigned char* lds, int l) {
;     ...
;             for (int dvb = 0; dvb < 8; ++dvb)
; #pragma unroll
;                 for (int rq = 0; rq < 4; ++rq) { const int dv = dvb * 32 + 8 * rq + 4 * hi; const u32x2 zz = *(const u32x2*)(zp + dv); const f32x4 g4 = *(const f32x4*)(gn + dv);
;                     const float y0 = o[dvb][rq * 4 + 0] * rs * g4[0] * siluf_(bf_lo(zz.x)), y1 = o[dvb][rq * 4 + 1] * rs * g4[1] * siluf_(bf_hi(zz.x));
;                     const float y2 = o[dvb][rq * 4 + 2] * rs * g4[2] * siluf_(bf_lo(zz.y)), y3 = o[dvb][rq * 4 + 3] * rs * g4[3] * siluf_(bf_hi(zz.y));
;                     u32x2 w; w.x = cvt_pk_bf16(y0, y1); w.y = cvt_pk_bf16(y2, y3); *(u32x2*)(zp + dv) = w; }
	v_mov_b32_e32 v102, v200
	v_mov_b32_e32 v103, v201
	v_lshlrev_b32_e32 v115, 16, v102
	v_mul_f32_e32 v105, 0xbfb8aa3b, v115
	v_exp_f32_e32 v105, v105
	s_waitcnt lgkmcnt(0)
	v_mov_b32_e32 v114, v98
	v_mov_b32_e32 v106, v99
	v_add_f32_e32 v105, 1.0, v105
	v_rcp_f32_e32 v105, v105
	s_nop 0
	v_pk_mul_f32 v[104:105], v[104:105], v[114:115]
	s_nop 0
	v_mul_f32_e32 v114, v104, v105
	v_mul_f32_e32 v104, v107, v140
	v_and_b32_e32 v107, 0xffff0000, v102
	v_mul_f32_e32 v98, 0xbfb8aa3b, v107
	v_exp_f32_e32 v98, v98
	v_mov_b32_e32 v102, v101
	v_add_f32_e32 v98, 1.0, v98
	v_rcp_f32_e32 v105, v98
	s_nop 0
	v_pk_mul_f32 v[98:99], v[104:105], v[106:107]
	v_lshlrev_b32_e32 v105, 16, v103
	v_mul_f32_e32 v106, v98, v99
	v_mul_f32_e32 v99, 0xbfb8aa3b, v105
	v_exp_f32_e32 v99, v99
	v_mul_f32_e32 v98, v108, v140
	v_mov_b32_e32 v104, v100
	v_and_b32_e32 v103, 0xffff0000, v103
	v_add_f32_e32 v99, 1.0, v99
	v_rcp_f32_e32 v99, v99
	s_nop 0
	v_pk_mul_f32 v[98:99], v[98:99], v[104:105]
	s_nop 0
	v_mul_f32_e32 v100, v98, v99
	v_mul_f32_e32 v99, 0xbfb8aa3b, v103
	v_exp_f32_e32 v99, v99
	v_mul_f32_e32 v98, v109, v140
	v_mul_f32_e32 v104, v110, v140
	v_add_f32_e32 v99, 1.0, v99
	v_rcp_f32_e32 v99, v99
	s_nop 0
	v_pk_mul_f32 v[98:99], v[98:99], v[102:103]
	s_nop 0
	v_mul_f32_e32 v99, v98, v99
	v_cvt_pk_bf16_f32 v98, v114, v106
	v_cvt_pk_bf16_f32 v99, v100, v99
	global_store_dwordx2 v[134:135], v[98:99], off offset:96
	s_nop 0
	ds_read_b128 v[98:101], v242 offset:224
	s_waitcnt vmcnt(31)
	v_mov_b32_e32 v102, v202
	v_mov_b32_e32 v103, v203
	v_lshlrev_b32_e32 v107, 16, v102
	v_mul_f32_e32 v105, 0xbfb8aa3b, v107
	v_exp_f32_e32 v105, v105
	s_waitcnt lgkmcnt(0)
	v_mov_b32_e32 v106, v98
	v_add_f32_e32 v105, 1.0, v105
	v_rcp_f32_e32 v105, v105
	s_nop 0
	v_pk_mul_f32 v[104:105], v[104:105], v[106:107]
	v_and_b32_e32 v107, 0xffff0000, v102
	v_mul_f32_e32 v98, 0xbfb8aa3b, v107
	v_exp_f32_e32 v98, v98
	v_mul_f32_e32 v108, v104, v105
	v_mul_f32_e32 v104, v111, v140
	v_mov_b32_e32 v106, v99
	v_add_f32_e32 v98, 1.0, v98
	v_rcp_f32_e32 v105, v98
	v_mov_b32_e32 v102, v101
	v_pk_mul_f32 v[98:99], v[104:105], v[106:107]
	v_lshlrev_b32_e32 v105, 16, v103
	v_mul_f32_e32 v106, v98, v99
	v_mul_f32_e32 v99, 0xbfb8aa3b, v105
	v_exp_f32_e32 v99, v99
	v_mul_f32_e32 v98, v112, v140
	v_mov_b32_e32 v104, v100
	v_and_b32_e32 v103, 0xffff0000, v103
	v_add_f32_e32 v99, 1.0, v99
	v_rcp_f32_e32 v99, v99
	s_nop 0
	v_pk_mul_f32 v[98:99], v[98:99], v[104:105]
	s_nop 0
	v_mul_f32_e32 v100, v98, v99
	v_mul_f32_e32 v99, 0xbfb8aa3b, v103
	v_exp_f32_e32 v99, v99
	v_mul_f32_e32 v98, v113, v140
	v_mul_f32_e32 v104, v82, v140
	v_add_f32_e32 v99, 1.0, v99
	v_rcp_f32_e32 v99, v99
	s_nop 0
	v_pk_mul_f32 v[98:99], v[98:99], v[102:103]
	s_nop 0
	v_mul_f32_e32 v99, v98, v99
	v_cvt_pk_bf16_f32 v98, v108, v106
	v_cvt_pk_bf16_f32 v99, v100, v99
	global_store_dwordx2 v[134:135], v[98:99], off offset:112
	s_nop 0
	ds_read_b128 v[98:101], v242 offset:256
	s_waitcnt vmcnt(31)
	v_mov_b32_e32 v102, v204
	v_mov_b32_e32 v103, v205
	v_lshlrev_b32_e32 v107, 16, v102
	v_mul_f32_e32 v82, 0xbfb8aa3b, v107
	v_exp_f32_e32 v82, v82
	s_waitcnt lgkmcnt(0)
	v_mov_b32_e32 v106, v98
	v_mov_b32_e32 v98, v100
	v_mul_f32_e32 v100, v86, v140
	v_add_f32_e32 v82, 1.0, v82
	v_rcp_f32_e32 v105, v82
	v_mul_f32_e32 v82, v83, v140
	v_pk_mul_f32 v[104:105], v[104:105], v[106:107]
	s_nop 0
	v_mul_f32_e32 v106, v104, v105
	v_and_b32_e32 v105, 0xffff0000, v102
	v_mul_f32_e32 v83, 0xbfb8aa3b, v105
	v_exp_f32_e32 v83, v83
	v_mov_b32_e32 v104, v99
	v_lshlrev_b32_e32 v99, 16, v103
	v_add_f32_e32 v83, 1.0, v83
	v_rcp_f32_e32 v83, v83
	s_nop 0
	v_pk_mul_f32 v[82:83], v[82:83], v[104:105]
	s_nop 0
	v_mul_f32_e32 v102, v82, v83
	v_mul_f32_e32 v83, 0xbfb8aa3b, v99
	v_exp_f32_e32 v83, v83
	v_mul_f32_e32 v82, v84, v140
	v_mov_b32_e32 v84, v101
	v_add_f32_e32 v83, 1.0, v83
	v_rcp_f32_e32 v83, v83
	s_nop 0
	v_pk_mul_f32 v[82:83], v[82:83], v[98:99]
	s_nop 0
	v_mul_f32_e32 v98, v82, v83
	v_mul_f32_e32 v82, v85, v140
	v_and_b32_e32 v85, 0xffff0000, v103
	v_mul_f32_e32 v83, 0xbfb8aa3b, v85
	v_exp_f32_e32 v83, v83
	s_nop 0
	v_add_f32_e32 v83, 1.0, v83
	v_rcp_f32_e32 v83, v83
	s_nop 0
	v_pk_mul_f32 v[82:83], v[82:83], v[84:85]
	s_nop 0
	v_mul_f32_e32 v83, v82, v83
	v_cvt_pk_bf16_f32 v82, v106, v102
	v_cvt_pk_bf16_f32 v83, v98, v83
	global_store_dwordx2 v[134:135], v[82:83], off offset:128
	s_nop 0
	ds_read_b128 v[82:85], v242 offset:288
	s_waitcnt vmcnt(31)
	v_mov_b32_e32 v98, v206
	v_mov_b32_e32 v99, v207
	v_lshlrev_b32_e32 v103, 16, v98
	v_mul_f32_e32 v86, 0xbfb8aa3b, v103
	v_exp_f32_e32 v86, v86
	s_waitcnt lgkmcnt(0)
	v_mov_b32_e32 v102, v82
	v_add_f32_e32 v86, 1.0, v86
	v_rcp_f32_e32 v101, v86
	v_mul_f32_e32 v86, v87, v140
	v_pk_mul_f32 v[100:101], v[100:101], v[102:103]
	s_nop 0
	v_mul_f32_e32 v102, v100, v101
	v_and_b32_e32 v101, 0xffff0000, v98
	v_mul_f32_e32 v82, 0xbfb8aa3b, v101
	v_exp_f32_e32 v82, v82
	v_mov_b32_e32 v100, v83
	v_add_f32_e32 v82, 1.0, v82
	v_rcp_f32_e32 v87, v82
	s_nop 0
	v_pk_mul_f32 v[82:83], v[86:87], v[100:101]
	v_lshlrev_b32_e32 v87, 16, v99
	v_mul_f32_e32 v98, v82, v83
	v_mul_f32_e32 v83, 0xbfb8aa3b, v87
	v_exp_f32_e32 v83, v83
	v_mul_f32_e32 v82, v88, v140
	v_mov_b32_e32 v86, v84
	v_mul_f32_e32 v88, v90, v140
	v_add_f32_e32 v83, 1.0, v83
	v_rcp_f32_e32 v83, v83
	s_nop 0
	v_pk_mul_f32 v[82:83], v[82:83], v[86:87]
	v_and_b32_e32 v87, 0xffff0000, v99
	v_mul_f32_e32 v84, v82, v83
	v_mul_f32_e32 v83, 0xbfb8aa3b, v87
	v_exp_f32_e32 v83, v83
	v_mul_f32_e32 v82, v89, v140
	v_mov_b32_e32 v86, v85
	v_add_f32_e32 v83, 1.0, v83
	v_rcp_f32_e32 v83, v83
	s_nop 0
	v_pk_mul_f32 v[82:83], v[82:83], v[86:87]
	s_nop 0
	v_mul_f32_e32 v83, v82, v83
	v_cvt_pk_bf16_f32 v82, v102, v98
	v_cvt_pk_bf16_f32 v83, v84, v83
	global_store_dwordx2 v[134:135], v[82:83], off offset:144
	s_nop 0
	ds_read_b128 v[82:85], v242 offset:320
	s_waitcnt vmcnt(31)
; __device__ __forceinline__ unsigned cvt_pk_bf16(float lo, float hi) { unsigned r; asm volatile("v_cvt_pk_bf16_f32 %0, %1, %2" : "=v"(r) : "v"(lo), "v"(hi)); return r; }
; __device__ __forceinline__ float bf_lo(unsigned w) { return __uint_as_float(w << 16); }
; __device__ __forceinline__ float bf_hi(unsigned w) { return __uint_as_float(w & 0xffff0000u); }
; __device__ __forceinline__ float siluf_(float v) { return v * sigmoidf_(v); }
; __device__ __forceinline__ void gla_out(const Params& p, LAS unsigned char* lds, int l) {
;     ...
;             for (int dvb = 0; dvb < 8; ++dvb)
; #pragma unroll
;                 for (int rq = 0; rq < 4; ++rq) { const int dv = dvb * 32 + 8 * rq + 4 * hi; const u32x2 zz = *(const u32x2*)(zp + dv); const f32x4 g4 = *(const f32x4*)(gn + dv);
;                     const float y0 = o[dvb][rq * 4 + 0] * rs * g4[0] * siluf_(bf_lo(zz.x)), y1 = o[dvb][rq * 4 + 1] * rs * g4[1] * siluf_(bf_hi(zz.x));
;                     const float y2 = o[dvb][rq * 4 + 2] * rs * g4[2] * siluf_(bf_lo(zz.y)), y3 = o[dvb][rq * 4 + 3] * rs * g4[3] * siluf_(bf_hi(zz.y));
;                     u32x2 w; w.x = cvt_pk_bf16(y0, y1); w.y = cvt_pk_bf16(y2, y3); *(u32x2*)(zp + dv) = w; }
	v_mov_b32_e32 v86, v208
	v_mov_b32_e32 v87, v209
	v_lshlrev_b32_e32 v99, 16, v86
	v_mul_f32_e32 v89, 0xbfb8aa3b, v99
	v_exp_f32_e32 v89, v89
	s_waitcnt lgkmcnt(0)
	v_mov_b32_e32 v98, v82
	v_mov_b32_e32 v90, v83
	v_add_f32_e32 v89, 1.0, v89
	v_rcp_f32_e32 v89, v89
	s_nop 0
	v_pk_mul_f32 v[88:89], v[88:89], v[98:99]
	s_nop 0
	v_mul_f32_e32 v98, v88, v89
	v_mul_f32_e32 v88, v91, v140
	v_and_b32_e32 v91, 0xffff0000, v86
	v_mul_f32_e32 v82, 0xbfb8aa3b, v91
	v_exp_f32_e32 v82, v82
	v_mov_b32_e32 v86, v85
	v_add_f32_e32 v82, 1.0, v82
	v_rcp_f32_e32 v89, v82
	s_nop 0
	v_pk_mul_f32 v[82:83], v[88:89], v[90:91]
	v_lshlrev_b32_e32 v89, 16, v87
	v_mul_f32_e32 v90, v82, v83
	v_mul_f32_e32 v83, 0xbfb8aa3b, v89
	v_exp_f32_e32 v83, v83
	v_mul_f32_e32 v82, v92, v140
	v_mov_b32_e32 v88, v84
	v_and_b32_e32 v87, 0xffff0000, v87
	v_add_f32_e32 v83, 1.0, v83
	v_rcp_f32_e32 v83, v83
	s_nop 0
	v_pk_mul_f32 v[82:83], v[82:83], v[88:89]
	s_nop 0
	v_mul_f32_e32 v84, v82, v83
	v_mul_f32_e32 v83, 0xbfb8aa3b, v87
	v_exp_f32_e32 v83, v83
	v_mul_f32_e32 v82, v93, v140
	v_mul_f32_e32 v88, v94, v140
	v_add_f32_e32 v83, 1.0, v83
	v_rcp_f32_e32 v83, v83
	s_nop 0
	v_pk_mul_f32 v[82:83], v[82:83], v[86:87]
	s_nop 0
	v_mul_f32_e32 v83, v82, v83
	v_cvt_pk_bf16_f32 v82, v98, v90
	v_cvt_pk_bf16_f32 v83, v84, v83
	global_store_dwordx2 v[134:135], v[82:83], off offset:160
	s_nop 0
	ds_read_b128 v[82:85], v242 offset:352
	s_waitcnt vmcnt(31)
	v_mov_b32_e32 v86, v210
	v_mov_b32_e32 v87, v211
	v_lshlrev_b32_e32 v91, 16, v86
	v_mul_f32_e32 v89, 0xbfb8aa3b, v91
	v_exp_f32_e32 v89, v89
	s_waitcnt lgkmcnt(0)
	v_mov_b32_e32 v90, v82
	v_add_f32_e32 v89, 1.0, v89
	v_rcp_f32_e32 v89, v89
	s_nop 0
	v_pk_mul_f32 v[88:89], v[88:89], v[90:91]
	v_and_b32_e32 v91, 0xffff0000, v86
	v_mul_f32_e32 v82, 0xbfb8aa3b, v91
	v_exp_f32_e32 v82, v82
	v_mul_f32_e32 v92, v88, v89
	v_mul_f32_e32 v88, v95, v140
	v_mov_b32_e32 v90, v83
	v_add_f32_e32 v82, 1.0, v82
	v_rcp_f32_e32 v89, v82
	v_mov_b32_e32 v86, v85
	v_pk_mul_f32 v[82:83], v[88:89], v[90:91]
	v_lshlrev_b32_e32 v89, 16, v87
	v_mul_f32_e32 v90, v82, v83
	v_mul_f32_e32 v83, 0xbfb8aa3b, v89
	v_exp_f32_e32 v83, v83
	v_mul_f32_e32 v82, v96, v140
	v_mov_b32_e32 v88, v84
	v_and_b32_e32 v87, 0xffff0000, v87
	v_add_f32_e32 v83, 1.0, v83
	v_rcp_f32_e32 v83, v83
	s_nop 0
	v_pk_mul_f32 v[82:83], v[82:83], v[88:89]
	s_nop 0
	v_mul_f32_e32 v84, v82, v83
	v_mul_f32_e32 v83, 0xbfb8aa3b, v87
	v_exp_f32_e32 v83, v83
	v_mul_f32_e32 v82, v97, v140
	v_mul_f32_e32 v88, v66, v140
	v_add_f32_e32 v83, 1.0, v83
	v_rcp_f32_e32 v83, v83
	s_nop 0
	v_pk_mul_f32 v[82:83], v[82:83], v[86:87]
	s_nop 0
	v_mul_f32_e32 v83, v82, v83
	v_cvt_pk_bf16_f32 v82, v92, v90
	v_cvt_pk_bf16_f32 v83, v84, v83
	global_store_dwordx2 v[134:135], v[82:83], off offset:176
	s_nop 0
	ds_read_b128 v[82:85], v242 offset:384
	s_waitcnt vmcnt(31)
	v_mov_b32_e32 v86, v212
	v_mov_b32_e32 v87, v213
	v_lshlrev_b32_e32 v91, 16, v86
	v_mul_f32_e32 v66, 0xbfb8aa3b, v91
	v_exp_f32_e32 v66, v66
	s_waitcnt lgkmcnt(0)
	v_mov_b32_e32 v90, v82
	v_mov_b32_e32 v82, v84
	v_mul_f32_e32 v84, v70, v140
	v_add_f32_e32 v66, 1.0, v66
	v_rcp_f32_e32 v89, v66
	v_mul_f32_e32 v66, v67, v140
	v_pk_mul_f32 v[88:89], v[88:89], v[90:91]
	s_nop 0
	v_mul_f32_e32 v90, v88, v89
	v_and_b32_e32 v89, 0xffff0000, v86
	v_mul_f32_e32 v67, 0xbfb8aa3b, v89
	v_exp_f32_e32 v67, v67
	v_mov_b32_e32 v88, v83
	v_lshlrev_b32_e32 v83, 16, v87
	v_add_f32_e32 v67, 1.0, v67
	v_rcp_f32_e32 v67, v67
	s_nop 0
	v_pk_mul_f32 v[66:67], v[66:67], v[88:89]
	s_nop 0
	v_mul_f32_e32 v86, v66, v67
	v_mul_f32_e32 v67, 0xbfb8aa3b, v83
	v_exp_f32_e32 v67, v67
	v_mul_f32_e32 v66, v68, v140
	v_mov_b32_e32 v68, v85
	v_add_f32_e32 v67, 1.0, v67
	v_rcp_f32_e32 v67, v67
	s_nop 0
	v_pk_mul_f32 v[66:67], v[66:67], v[82:83]
	s_nop 0
	v_mul_f32_e32 v82, v66, v67
	v_mul_f32_e32 v66, v69, v140
	v_and_b32_e32 v69, 0xffff0000, v87
	v_mul_f32_e32 v67, 0xbfb8aa3b, v69
	v_exp_f32_e32 v67, v67
	s_nop 0
	v_add_f32_e32 v67, 1.0, v67
	v_rcp_f32_e32 v67, v67
	s_nop 0
	v_pk_mul_f32 v[66:67], v[66:67], v[68:69]
	s_nop 0
	v_mul_f32_e32 v67, v66, v67
	v_cvt_pk_bf16_f32 v66, v90, v86
	v_cvt_pk_bf16_f32 v67, v82, v67
	global_store_dwordx2 v[134:135], v[66:67], off offset:192
	s_nop 0
	ds_read_b128 v[66:69], v242 offset:416
	s_waitcnt vmcnt(31)
	v_mov_b32_e32 v82, v214
	v_mov_b32_e32 v83, v215
	v_lshlrev_b32_e32 v87, 16, v82
	v_mul_f32_e32 v70, 0xbfb8aa3b, v87
	v_exp_f32_e32 v70, v70
	s_waitcnt lgkmcnt(0)
	v_mov_b32_e32 v86, v66
	v_add_f32_e32 v70, 1.0, v70
	v_rcp_f32_e32 v85, v70
	v_mul_f32_e32 v70, v71, v140
	v_pk_mul_f32 v[84:85], v[84:85], v[86:87]
	s_nop 0
	v_mul_f32_e32 v86, v84, v85
	v_and_b32_e32 v85, 0xffff0000, v82
	v_mul_f32_e32 v66, 0xbfb8aa3b, v85
	v_exp_f32_e32 v66, v66
	v_mov_b32_e32 v84, v67
	v_add_f32_e32 v66, 1.0, v66
	v_rcp_f32_e32 v71, v66
	s_nop 0
	v_pk_mul_f32 v[66:67], v[70:71], v[84:85]
	v_lshlrev_b32_e32 v71, 16, v83
	v_mul_f32_e32 v82, v66, v67
	v_mul_f32_e32 v67, 0xbfb8aa3b, v71
	v_exp_f32_e32 v67, v67
	v_mul_f32_e32 v66, v72, v140
	v_mov_b32_e32 v70, v68
	v_mul_f32_e32 v72, v74, v140
	v_add_f32_e32 v67, 1.0, v67
	v_rcp_f32_e32 v67, v67
	s_nop 0
	v_pk_mul_f32 v[66:67], v[66:67], v[70:71]
	v_and_b32_e32 v71, 0xffff0000, v83
	v_mul_f32_e32 v68, v66, v67
	v_mul_f32_e32 v67, 0xbfb8aa3b, v71
	v_exp_f32_e32 v67, v67
	v_mul_f32_e32 v66, v73, v140
	v_mov_b32_e32 v70, v69
	v_add_f32_e32 v67, 1.0, v67
	v_rcp_f32_e32 v67, v67
	s_nop 0
	v_pk_mul_f32 v[66:67], v[66:67], v[70:71]
	s_nop 0
	v_mul_f32_e32 v67, v66, v67
	v_cvt_pk_bf16_f32 v66, v86, v82
	v_cvt_pk_bf16_f32 v67, v68, v67
	global_store_dwordx2 v[134:135], v[66:67], off offset:208
	s_nop 0
	ds_read_b128 v[66:69], v242 offset:448
	s_waitcnt vmcnt(31)
; __device__ __forceinline__ unsigned cvt_pk_bf16(float lo, float hi) { unsigned r; asm volatile("v_cvt_pk_bf16_f32 %0, %1, %2" : "=v"(r) : "v"(lo), "v"(hi)); return r; }
; __device__ __forceinline__ float bf_lo(unsigned w) { return __uint_as_float(w << 16); }
; __device__ __forceinline__ float bf_hi(unsigned w) { return __uint_as_float(w & 0xffff0000u); }
; __device__ __forceinline__ float siluf_(float v) { return v * sigmoidf_(v); }
; __device__ __forceinline__ void gla_out(const Params& p, LAS unsigned char* lds, int l) {
;     ...
;             for (int dvb = 0; dvb < 8; ++dvb)
; #pragma unroll
;                 for (int rq = 0; rq < 4; ++rq) { const int dv = dvb * 32 + 8 * rq + 4 * hi; const u32x2 zz = *(const u32x2*)(zp + dv); const f32x4 g4 = *(const f32x4*)(gn + dv);
;                     const float y0 = o[dvb][rq * 4 + 0] * rs * g4[0] * siluf_(bf_lo(zz.x)), y1 = o[dvb][rq * 4 + 1] * rs * g4[1] * siluf_(bf_hi(zz.x));
;                     const float y2 = o[dvb][rq * 4 + 2] * rs * g4[2] * siluf_(bf_lo(zz.y)), y3 = o[dvb][rq * 4 + 3] * rs * g4[3] * siluf_(bf_hi(zz.y));
;                     u32x2 w; w.x = cvt_pk_bf16(y0, y1); w.y = cvt_pk_bf16(y2, y3); *(u32x2*)(zp + dv) = w; }
	v_mov_b32_e32 v70, v218
	v_mov_b32_e32 v71, v219
	v_lshlrev_b32_e32 v83, 16, v70
	v_mul_f32_e32 v73, 0xbfb8aa3b, v83
	v_exp_f32_e32 v73, v73
	s_waitcnt lgkmcnt(0)
	v_mov_b32_e32 v82, v66
	v_mov_b32_e32 v74, v67
	v_add_f32_e32 v73, 1.0, v73
	v_rcp_f32_e32 v73, v73
	s_nop 0
	v_pk_mul_f32 v[72:73], v[72:73], v[82:83]
	s_nop 0
	v_mul_f32_e32 v82, v72, v73
	v_mul_f32_e32 v72, v75, v140
	v_and_b32_e32 v75, 0xffff0000, v70
	v_mul_f32_e32 v66, 0xbfb8aa3b, v75
	v_exp_f32_e32 v66, v66
	v_mov_b32_e32 v70, v69
	v_add_f32_e32 v66, 1.0, v66
	v_rcp_f32_e32 v73, v66
	s_nop 0
	v_pk_mul_f32 v[66:67], v[72:73], v[74:75]
	v_lshlrev_b32_e32 v73, 16, v71
	v_mul_f32_e32 v74, v66, v67
	v_mul_f32_e32 v67, 0xbfb8aa3b, v73
	v_exp_f32_e32 v67, v67
	v_mul_f32_e32 v66, v76, v140
	v_mov_b32_e32 v72, v68
	v_and_b32_e32 v71, 0xffff0000, v71
	v_add_f32_e32 v67, 1.0, v67
	v_rcp_f32_e32 v67, v67
	s_nop 0
	v_pk_mul_f32 v[66:67], v[66:67], v[72:73]
	s_nop 0
	v_mul_f32_e32 v68, v66, v67
	v_mul_f32_e32 v67, 0xbfb8aa3b, v71
	v_exp_f32_e32 v67, v67
	v_mul_f32_e32 v66, v77, v140
	v_mul_f32_e32 v72, v78, v140
	v_add_f32_e32 v67, 1.0, v67
	v_rcp_f32_e32 v67, v67
	s_nop 0
	v_pk_mul_f32 v[66:67], v[66:67], v[70:71]
	s_nop 0
	v_mul_f32_e32 v67, v66, v67
	v_cvt_pk_bf16_f32 v66, v82, v74
	v_cvt_pk_bf16_f32 v67, v68, v67
	global_store_dwordx2 v[134:135], v[66:67], off offset:224
	s_nop 0
	ds_read_b128 v[66:69], v242 offset:480
	s_waitcnt vmcnt(31)
	v_mov_b32_e32 v70, v220
	v_mov_b32_e32 v71, v221
	v_lshlrev_b32_e32 v75, 16, v70
	v_mul_f32_e32 v73, 0xbfb8aa3b, v75
	v_exp_f32_e32 v73, v73
	s_waitcnt lgkmcnt(0)
	v_mov_b32_e32 v74, v66
	v_add_f32_e32 v73, 1.0, v73
	v_rcp_f32_e32 v73, v73
	s_nop 0
	v_pk_mul_f32 v[72:73], v[72:73], v[74:75]
	v_and_b32_e32 v75, 0xffff0000, v70
	v_mul_f32_e32 v66, 0xbfb8aa3b, v75
	v_exp_f32_e32 v66, v66
	v_mul_f32_e32 v76, v72, v73
	v_mul_f32_e32 v72, v79, v140
	v_mov_b32_e32 v74, v67
	v_add_f32_e32 v66, 1.0, v66
	v_rcp_f32_e32 v73, v66
	v_mov_b32_e32 v70, v69
	v_pk_mul_f32 v[66:67], v[72:73], v[74:75]
	v_lshlrev_b32_e32 v73, 16, v71
	v_mul_f32_e32 v74, v66, v67
	v_mul_f32_e32 v67, 0xbfb8aa3b, v73
	v_exp_f32_e32 v67, v67
	v_mul_f32_e32 v66, v80, v140
	v_mov_b32_e32 v72, v68
	v_and_b32_e32 v71, 0xffff0000, v71
	v_add_f32_e32 v67, 1.0, v67
	v_rcp_f32_e32 v67, v67
	s_nop 0
	v_pk_mul_f32 v[66:67], v[66:67], v[72:73]
	s_nop 0
	v_mul_f32_e32 v68, v66, v67
	v_mul_f32_e32 v67, 0xbfb8aa3b, v71
	v_exp_f32_e32 v67, v67
	v_mul_f32_e32 v66, v81, v140
	v_mul_f32_e32 v72, v50, v140
	v_add_f32_e32 v67, 1.0, v67
	v_rcp_f32_e32 v67, v67
	s_nop 0
	v_pk_mul_f32 v[66:67], v[66:67], v[70:71]
	s_nop 0
	v_mul_f32_e32 v67, v66, v67
	v_cvt_pk_bf16_f32 v66, v76, v74
	v_cvt_pk_bf16_f32 v67, v68, v67
	global_store_dwordx2 v[134:135], v[66:67], off offset:240
	s_nop 0
	ds_read_b128 v[66:69], v242 offset:512
	s_waitcnt vmcnt(31)
	v_mov_b32_e32 v70, v146
	v_mov_b32_e32 v71, v147
	v_lshlrev_b32_e32 v75, 16, v70
	v_mul_f32_e32 v50, 0xbfb8aa3b, v75
	v_exp_f32_e32 v50, v50
	s_waitcnt lgkmcnt(0)
	v_mov_b32_e32 v74, v66
	v_mov_b32_e32 v66, v68
	v_mul_f32_e32 v68, v54, v140
	v_add_f32_e32 v50, 1.0, v50
	v_rcp_f32_e32 v73, v50
	v_mul_f32_e32 v50, v51, v140
	v_pk_mul_f32 v[72:73], v[72:73], v[74:75]
	s_nop 0
	v_mul_f32_e32 v74, v72, v73
	v_and_b32_e32 v73, 0xffff0000, v70
	v_mul_f32_e32 v51, 0xbfb8aa3b, v73
	v_exp_f32_e32 v51, v51
	v_mov_b32_e32 v72, v67
	v_lshlrev_b32_e32 v67, 16, v71
	v_add_f32_e32 v51, 1.0, v51
	v_rcp_f32_e32 v51, v51
	s_nop 0
	v_pk_mul_f32 v[50:51], v[50:51], v[72:73]
	s_nop 0
	v_mul_f32_e32 v70, v50, v51
	v_mul_f32_e32 v51, 0xbfb8aa3b, v67
	v_exp_f32_e32 v51, v51
	v_mul_f32_e32 v50, v52, v140
	v_mov_b32_e32 v52, v69
	v_add_f32_e32 v51, 1.0, v51
	v_rcp_f32_e32 v51, v51
	s_nop 0
	v_pk_mul_f32 v[50:51], v[50:51], v[66:67]
	s_nop 0
	v_mul_f32_e32 v66, v50, v51
	v_mul_f32_e32 v50, v53, v140
	v_and_b32_e32 v53, 0xffff0000, v71
	v_mul_f32_e32 v51, 0xbfb8aa3b, v53
	v_exp_f32_e32 v51, v51
	s_nop 0
	v_add_f32_e32 v51, 1.0, v51
	v_rcp_f32_e32 v51, v51
	s_nop 0
	v_pk_mul_f32 v[50:51], v[50:51], v[52:53]
	s_nop 0
	v_mul_f32_e32 v51, v50, v51
	v_cvt_pk_bf16_f32 v50, v74, v70
	v_cvt_pk_bf16_f32 v51, v66, v51
	global_store_dwordx2 v[134:135], v[50:51], off offset:256
	s_nop 0
	ds_read_b128 v[50:53], v242 offset:544
	s_waitcnt vmcnt(31)
	v_mov_b32_e32 v66, v148
	v_mov_b32_e32 v67, v149
	v_lshlrev_b32_e32 v71, 16, v66
	v_mul_f32_e32 v54, 0xbfb8aa3b, v71
	v_exp_f32_e32 v54, v54
	s_waitcnt lgkmcnt(0)
	v_mov_b32_e32 v70, v50
	v_add_f32_e32 v54, 1.0, v54
	v_rcp_f32_e32 v69, v54
	v_mul_f32_e32 v54, v55, v140
	v_pk_mul_f32 v[68:69], v[68:69], v[70:71]
	s_nop 0
	v_mul_f32_e32 v70, v68, v69
	v_and_b32_e32 v69, 0xffff0000, v66
	v_mul_f32_e32 v50, 0xbfb8aa3b, v69
	v_exp_f32_e32 v50, v50
	v_mov_b32_e32 v68, v51
	v_add_f32_e32 v50, 1.0, v50
	v_rcp_f32_e32 v55, v50
	s_nop 0
	v_pk_mul_f32 v[50:51], v[54:55], v[68:69]
	v_lshlrev_b32_e32 v55, 16, v67
	v_mul_f32_e32 v66, v50, v51
	v_mul_f32_e32 v51, 0xbfb8aa3b, v55
	v_exp_f32_e32 v51, v51
	v_mul_f32_e32 v50, v56, v140
	v_mov_b32_e32 v54, v52
	v_mul_f32_e32 v56, v58, v140
	v_add_f32_e32 v51, 1.0, v51
	v_rcp_f32_e32 v51, v51
	s_nop 0
	v_pk_mul_f32 v[50:51], v[50:51], v[54:55]
	v_and_b32_e32 v55, 0xffff0000, v67
	v_mul_f32_e32 v52, v50, v51
	v_mul_f32_e32 v51, 0xbfb8aa3b, v55
	v_exp_f32_e32 v51, v51
	v_mul_f32_e32 v50, v57, v140
	v_mov_b32_e32 v54, v53
	v_add_f32_e32 v51, 1.0, v51
	v_rcp_f32_e32 v51, v51
	s_nop 0
	v_pk_mul_f32 v[50:51], v[50:51], v[54:55]
	s_nop 0
	v_mul_f32_e32 v51, v50, v51
	v_cvt_pk_bf16_f32 v50, v70, v66
	v_cvt_pk_bf16_f32 v51, v52, v51
	global_store_dwordx2 v[134:135], v[50:51], off offset:272
	s_nop 0
	ds_read_b128 v[50:53], v242 offset:576
	s_waitcnt vmcnt(31)
; __device__ __forceinline__ unsigned cvt_pk_bf16(float lo, float hi) { unsigned r; asm volatile("v_cvt_pk_bf16_f32 %0, %1, %2" : "=v"(r) : "v"(lo), "v"(hi)); return r; }
; __device__ __forceinline__ float bf_lo(unsigned w) { return __uint_as_float(w << 16); }
; __device__ __forceinline__ float bf_hi(unsigned w) { return __uint_as_float(w & 0xffff0000u); }
; __device__ __forceinline__ float siluf_(float v) { return v * sigmoidf_(v); }
; __device__ __forceinline__ void gla_out(const Params& p, LAS unsigned char* lds, int l) {
;     ...
;             for (int dvb = 0; dvb < 8; ++dvb)
; #pragma unroll
;                 for (int rq = 0; rq < 4; ++rq) { const int dv = dvb * 32 + 8 * rq + 4 * hi; const u32x2 zz = *(const u32x2*)(zp + dv); const f32x4 g4 = *(const f32x4*)(gn + dv);
;                     const float y0 = o[dvb][rq * 4 + 0] * rs * g4[0] * siluf_(bf_lo(zz.x)), y1 = o[dvb][rq * 4 + 1] * rs * g4[1] * siluf_(bf_hi(zz.x));
;                     const float y2 = o[dvb][rq * 4 + 2] * rs * g4[2] * siluf_(bf_lo(zz.y)), y3 = o[dvb][rq * 4 + 3] * rs * g4[3] * siluf_(bf_hi(zz.y));
;                     u32x2 w; w.x = cvt_pk_bf16(y0, y1); w.y = cvt_pk_bf16(y2, y3); *(u32x2*)(zp + dv) = w; }
	v_mov_b32_e32 v54, v150
	v_mov_b32_e32 v55, v151
	v_lshlrev_b32_e32 v67, 16, v54
	v_mul_f32_e32 v57, 0xbfb8aa3b, v67
	v_exp_f32_e32 v57, v57
	s_waitcnt lgkmcnt(0)
	v_mov_b32_e32 v66, v50
	v_mov_b32_e32 v58, v51
	v_add_f32_e32 v57, 1.0, v57
	v_rcp_f32_e32 v57, v57
	s_nop 0
	v_pk_mul_f32 v[56:57], v[56:57], v[66:67]
	s_nop 0
	v_mul_f32_e32 v66, v56, v57
	v_mul_f32_e32 v56, v59, v140
	v_and_b32_e32 v59, 0xffff0000, v54
	v_mul_f32_e32 v50, 0xbfb8aa3b, v59
	v_exp_f32_e32 v50, v50
	v_mov_b32_e32 v54, v53
	v_add_f32_e32 v50, 1.0, v50
	v_rcp_f32_e32 v57, v50
	s_nop 0
	v_pk_mul_f32 v[50:51], v[56:57], v[58:59]
	v_lshlrev_b32_e32 v57, 16, v55
	v_mul_f32_e32 v58, v50, v51
	v_mul_f32_e32 v51, 0xbfb8aa3b, v57
	v_exp_f32_e32 v51, v51
	v_mul_f32_e32 v50, v60, v140
	v_mov_b32_e32 v56, v52
	v_and_b32_e32 v55, 0xffff0000, v55
	v_add_f32_e32 v51, 1.0, v51
	v_rcp_f32_e32 v51, v51
	s_nop 0
	v_pk_mul_f32 v[50:51], v[50:51], v[56:57]
	s_nop 0
	v_mul_f32_e32 v52, v50, v51
	v_mul_f32_e32 v51, 0xbfb8aa3b, v55
	v_exp_f32_e32 v51, v51
	v_mul_f32_e32 v50, v61, v140
	v_mul_f32_e32 v56, v62, v140
	v_add_f32_e32 v51, 1.0, v51
	v_rcp_f32_e32 v51, v51
	s_nop 0
	v_pk_mul_f32 v[50:51], v[50:51], v[54:55]
	s_nop 0
	v_mul_f32_e32 v51, v50, v51
	v_cvt_pk_bf16_f32 v50, v66, v58
	v_cvt_pk_bf16_f32 v51, v52, v51
	global_store_dwordx2 v[134:135], v[50:51], off offset:288
	s_nop 0
	ds_read_b128 v[50:53], v242 offset:608
	s_waitcnt vmcnt(31)
	v_mov_b32_e32 v54, v152
	v_mov_b32_e32 v55, v153
	v_lshlrev_b32_e32 v59, 16, v54
	v_mul_f32_e32 v57, 0xbfb8aa3b, v59
	v_exp_f32_e32 v57, v57
	s_waitcnt lgkmcnt(0)
	v_mov_b32_e32 v58, v50
	v_add_f32_e32 v57, 1.0, v57
	v_rcp_f32_e32 v57, v57
	s_nop 0
	v_pk_mul_f32 v[56:57], v[56:57], v[58:59]
	v_and_b32_e32 v59, 0xffff0000, v54
	v_mul_f32_e32 v50, 0xbfb8aa3b, v59
	v_exp_f32_e32 v50, v50
	v_mul_f32_e32 v60, v56, v57
	v_mul_f32_e32 v56, v63, v140
	v_mov_b32_e32 v58, v51
	v_add_f32_e32 v50, 1.0, v50
	v_rcp_f32_e32 v57, v50
	v_mov_b32_e32 v54, v53
	v_pk_mul_f32 v[50:51], v[56:57], v[58:59]
	v_lshlrev_b32_e32 v57, 16, v55
	v_mul_f32_e32 v58, v50, v51
	v_mul_f32_e32 v51, 0xbfb8aa3b, v57
	v_exp_f32_e32 v51, v51
	v_mul_f32_e32 v50, v64, v140
	v_mov_b32_e32 v56, v52
	v_and_b32_e32 v55, 0xffff0000, v55
	v_add_f32_e32 v51, 1.0, v51
	v_rcp_f32_e32 v51, v51
	s_nop 0
	v_pk_mul_f32 v[50:51], v[50:51], v[56:57]
	s_nop 0
	v_mul_f32_e32 v52, v50, v51
	v_mul_f32_e32 v51, 0xbfb8aa3b, v55
	v_exp_f32_e32 v51, v51
	v_mul_f32_e32 v50, v65, v140
	v_mul_f32_e32 v56, v34, v140
	v_add_f32_e32 v51, 1.0, v51
	v_rcp_f32_e32 v51, v51
	s_nop 0
	v_pk_mul_f32 v[50:51], v[50:51], v[54:55]
	s_nop 0
	v_mul_f32_e32 v51, v50, v51
	v_cvt_pk_bf16_f32 v50, v60, v58
	v_cvt_pk_bf16_f32 v51, v52, v51
	global_store_dwordx2 v[134:135], v[50:51], off offset:304
	s_nop 0
	ds_read_b128 v[50:53], v242 offset:640
	s_waitcnt vmcnt(31)
	v_mov_b32_e32 v54, v154
	v_mov_b32_e32 v55, v155
	v_lshlrev_b32_e32 v59, 16, v54
	v_mul_f32_e32 v34, 0xbfb8aa3b, v59
	v_exp_f32_e32 v34, v34
	s_waitcnt lgkmcnt(0)
	v_mov_b32_e32 v58, v50
	v_mov_b32_e32 v50, v52
	v_mul_f32_e32 v52, v38, v140
	v_add_f32_e32 v34, 1.0, v34
	v_rcp_f32_e32 v57, v34
	v_mul_f32_e32 v34, v35, v140
	v_pk_mul_f32 v[56:57], v[56:57], v[58:59]
	s_nop 0
	v_mul_f32_e32 v58, v56, v57
	v_and_b32_e32 v57, 0xffff0000, v54
	v_mul_f32_e32 v35, 0xbfb8aa3b, v57
	v_exp_f32_e32 v35, v35
	v_mov_b32_e32 v56, v51
	v_lshlrev_b32_e32 v51, 16, v55
	v_add_f32_e32 v35, 1.0, v35
	v_rcp_f32_e32 v35, v35
	s_nop 0
	v_pk_mul_f32 v[34:35], v[34:35], v[56:57]
	s_nop 0
	v_mul_f32_e32 v54, v34, v35
	v_mul_f32_e32 v35, 0xbfb8aa3b, v51
	v_exp_f32_e32 v35, v35
	v_mul_f32_e32 v34, v36, v140
	v_mov_b32_e32 v36, v53
	v_add_f32_e32 v35, 1.0, v35
	v_rcp_f32_e32 v35, v35
	s_nop 0
	v_pk_mul_f32 v[34:35], v[34:35], v[50:51]
	s_nop 0
	v_mul_f32_e32 v50, v34, v35
	v_mul_f32_e32 v34, v37, v140
	v_and_b32_e32 v37, 0xffff0000, v55
	v_mul_f32_e32 v35, 0xbfb8aa3b, v37
	v_exp_f32_e32 v35, v35
	s_nop 0
	v_add_f32_e32 v35, 1.0, v35
	v_rcp_f32_e32 v35, v35
	s_nop 0
	v_pk_mul_f32 v[34:35], v[34:35], v[36:37]
	s_nop 0
	v_mul_f32_e32 v35, v34, v35
	v_cvt_pk_bf16_f32 v34, v58, v54
	v_cvt_pk_bf16_f32 v35, v50, v35
	global_store_dwordx2 v[134:135], v[34:35], off offset:320
	s_nop 0
	ds_read_b128 v[34:37], v242 offset:672
	s_waitcnt vmcnt(31)
	v_mov_b32_e32 v50, v156
	v_mov_b32_e32 v51, v157
	v_lshlrev_b32_e32 v55, 16, v50
	v_mul_f32_e32 v38, 0xbfb8aa3b, v55
	v_exp_f32_e32 v38, v38
	s_waitcnt lgkmcnt(0)
	v_mov_b32_e32 v54, v34
	v_add_f32_e32 v38, 1.0, v38
	v_rcp_f32_e32 v53, v38
	v_mul_f32_e32 v38, v39, v140
	v_pk_mul_f32 v[52:53], v[52:53], v[54:55]
	s_nop 0
	v_mul_f32_e32 v54, v52, v53
	v_and_b32_e32 v53, 0xffff0000, v50
	v_mul_f32_e32 v34, 0xbfb8aa3b, v53
	v_exp_f32_e32 v34, v34
	v_mov_b32_e32 v52, v35
	v_add_f32_e32 v34, 1.0, v34
	v_rcp_f32_e32 v39, v34
	s_nop 0
	v_pk_mul_f32 v[34:35], v[38:39], v[52:53]
	v_lshlrev_b32_e32 v39, 16, v51
	v_mul_f32_e32 v50, v34, v35
	v_mul_f32_e32 v35, 0xbfb8aa3b, v39
	v_exp_f32_e32 v35, v35
	v_mul_f32_e32 v34, v40, v140
	v_mov_b32_e32 v38, v36
	v_mul_f32_e32 v40, v42, v140
	v_add_f32_e32 v35, 1.0, v35
	v_rcp_f32_e32 v35, v35
	s_nop 0
	v_pk_mul_f32 v[34:35], v[34:35], v[38:39]
	v_and_b32_e32 v39, 0xffff0000, v51
	v_mul_f32_e32 v36, v34, v35
	v_mul_f32_e32 v35, 0xbfb8aa3b, v39
	v_exp_f32_e32 v35, v35
	v_mul_f32_e32 v34, v41, v140
	v_mov_b32_e32 v38, v37
	v_add_f32_e32 v35, 1.0, v35
	v_rcp_f32_e32 v35, v35
	s_nop 0
	v_pk_mul_f32 v[34:35], v[34:35], v[38:39]
	s_nop 0
	v_mul_f32_e32 v35, v34, v35
	v_cvt_pk_bf16_f32 v34, v54, v50
	v_cvt_pk_bf16_f32 v35, v36, v35
	global_store_dwordx2 v[134:135], v[34:35], off offset:336
	s_nop 0
	ds_read_b128 v[34:37], v242 offset:704
	s_waitcnt vmcnt(31)
; __device__ __forceinline__ unsigned cvt_pk_bf16(float lo, float hi) { unsigned r; asm volatile("v_cvt_pk_bf16_f32 %0, %1, %2" : "=v"(r) : "v"(lo), "v"(hi)); return r; }
; __device__ __forceinline__ float bf_lo(unsigned w) { return __uint_as_float(w << 16); }
; __device__ __forceinline__ float bf_hi(unsigned w) { return __uint_as_float(w & 0xffff0000u); }
; __device__ __forceinline__ float siluf_(float v) { return v * sigmoidf_(v); }
; __device__ __forceinline__ void gla_out(const Params& p, LAS unsigned char* lds, int l) {
;     ...
;             for (int dvb = 0; dvb < 8; ++dvb)
; #pragma unroll
;                 for (int rq = 0; rq < 4; ++rq) { const int dv = dvb * 32 + 8 * rq + 4 * hi; const u32x2 zz = *(const u32x2*)(zp + dv); const f32x4 g4 = *(const f32x4*)(gn + dv);
;                     const float y0 = o[dvb][rq * 4 + 0] * rs * g4[0] * siluf_(bf_lo(zz.x)), y1 = o[dvb][rq * 4 + 1] * rs * g4[1] * siluf_(bf_hi(zz.x));
;                     const float y2 = o[dvb][rq * 4 + 2] * rs * g4[2] * siluf_(bf_lo(zz.y)), y3 = o[dvb][rq * 4 + 3] * rs * g4[3] * siluf_(bf_hi(zz.y));
;                     u32x2 w; w.x = cvt_pk_bf16(y0, y1); w.y = cvt_pk_bf16(y2, y3); *(u32x2*)(zp + dv) = w; }
	v_mov_b32_e32 v38, v158
	v_mov_b32_e32 v39, v159
	v_lshlrev_b32_e32 v51, 16, v38
	v_mul_f32_e32 v41, 0xbfb8aa3b, v51
	v_exp_f32_e32 v41, v41
	s_waitcnt lgkmcnt(0)
	v_mov_b32_e32 v50, v34
	v_mov_b32_e32 v42, v35
	v_add_f32_e32 v41, 1.0, v41
	v_rcp_f32_e32 v41, v41
	s_nop 0
	v_pk_mul_f32 v[40:41], v[40:41], v[50:51]
	s_nop 0
	v_mul_f32_e32 v50, v40, v41
	v_mul_f32_e32 v40, v43, v140
	v_and_b32_e32 v43, 0xffff0000, v38
	v_mul_f32_e32 v34, 0xbfb8aa3b, v43
	v_exp_f32_e32 v34, v34
	v_mov_b32_e32 v38, v37
	v_add_f32_e32 v34, 1.0, v34
	v_rcp_f32_e32 v41, v34
	s_nop 0
	v_pk_mul_f32 v[34:35], v[40:41], v[42:43]
	v_lshlrev_b32_e32 v41, 16, v39
	v_mul_f32_e32 v42, v34, v35
	v_mul_f32_e32 v35, 0xbfb8aa3b, v41
	v_exp_f32_e32 v35, v35
	v_mul_f32_e32 v34, v44, v140
	v_mov_b32_e32 v40, v36
	v_and_b32_e32 v39, 0xffff0000, v39
	v_add_f32_e32 v35, 1.0, v35
	v_rcp_f32_e32 v35, v35
	s_nop 0
	v_pk_mul_f32 v[34:35], v[34:35], v[40:41]
	s_nop 0
	v_mul_f32_e32 v36, v34, v35
	v_mul_f32_e32 v35, 0xbfb8aa3b, v39
	v_exp_f32_e32 v35, v35
	v_mul_f32_e32 v34, v45, v140
	v_mul_f32_e32 v40, v46, v140
	v_add_f32_e32 v35, 1.0, v35
	v_rcp_f32_e32 v35, v35
	s_nop 0
	v_pk_mul_f32 v[34:35], v[34:35], v[38:39]
	s_nop 0
	v_mul_f32_e32 v35, v34, v35
	v_cvt_pk_bf16_f32 v34, v50, v42
	v_cvt_pk_bf16_f32 v35, v36, v35
	global_store_dwordx2 v[134:135], v[34:35], off offset:352
	s_nop 0
	ds_read_b128 v[34:37], v242 offset:736
	s_waitcnt vmcnt(31)
	v_mov_b32_e32 v38, v160
	v_mov_b32_e32 v39, v161
	v_lshlrev_b32_e32 v43, 16, v38
	v_mul_f32_e32 v41, 0xbfb8aa3b, v43
	v_exp_f32_e32 v41, v41
	s_waitcnt lgkmcnt(0)
	v_mov_b32_e32 v42, v34
	v_add_f32_e32 v41, 1.0, v41
	v_rcp_f32_e32 v41, v41
	s_nop 0
	v_pk_mul_f32 v[40:41], v[40:41], v[42:43]
	v_and_b32_e32 v43, 0xffff0000, v38
	v_mul_f32_e32 v34, 0xbfb8aa3b, v43
	v_exp_f32_e32 v34, v34
	v_mul_f32_e32 v44, v40, v41
	v_mul_f32_e32 v40, v47, v140
	v_mov_b32_e32 v42, v35
	v_add_f32_e32 v34, 1.0, v34
	v_rcp_f32_e32 v41, v34
	v_mov_b32_e32 v38, v37
	v_pk_mul_f32 v[34:35], v[40:41], v[42:43]
	v_lshlrev_b32_e32 v41, 16, v39
	v_mul_f32_e32 v42, v34, v35
	v_mul_f32_e32 v35, 0xbfb8aa3b, v41
	v_exp_f32_e32 v35, v35
	v_mul_f32_e32 v34, v48, v140
	v_mov_b32_e32 v40, v36
	v_and_b32_e32 v39, 0xffff0000, v39
	v_add_f32_e32 v35, 1.0, v35
	v_rcp_f32_e32 v35, v35
	s_nop 0
	v_pk_mul_f32 v[34:35], v[34:35], v[40:41]
	s_nop 0
	v_mul_f32_e32 v36, v34, v35
	v_mul_f32_e32 v35, 0xbfb8aa3b, v39
	v_exp_f32_e32 v35, v35
	v_mul_f32_e32 v34, v49, v140
	v_mul_f32_e32 v40, v18, v140
	v_add_f32_e32 v35, 1.0, v35
	v_rcp_f32_e32 v35, v35
	s_nop 0
	v_pk_mul_f32 v[34:35], v[34:35], v[38:39]
	s_nop 0
	v_mul_f32_e32 v35, v34, v35
	v_cvt_pk_bf16_f32 v34, v44, v42
	v_cvt_pk_bf16_f32 v35, v36, v35
	global_store_dwordx2 v[134:135], v[34:35], off offset:368
	s_nop 0
	ds_read_b128 v[34:37], v242 offset:768
	s_waitcnt vmcnt(31)
	v_mov_b32_e32 v38, v226
	v_mov_b32_e32 v39, v227
	v_lshlrev_b32_e32 v43, 16, v38
	v_mul_f32_e32 v18, 0xbfb8aa3b, v43
	v_exp_f32_e32 v18, v18
	s_waitcnt lgkmcnt(0)
	v_mov_b32_e32 v42, v34
	v_mov_b32_e32 v34, v36
	v_mul_f32_e32 v36, v22, v140
	v_add_f32_e32 v18, 1.0, v18
	v_rcp_f32_e32 v41, v18
	v_mul_f32_e32 v18, v19, v140
	v_pk_mul_f32 v[40:41], v[40:41], v[42:43]
	s_nop 0
	v_mul_f32_e32 v42, v40, v41
	v_and_b32_e32 v41, 0xffff0000, v38
	v_mul_f32_e32 v19, 0xbfb8aa3b, v41
	v_exp_f32_e32 v19, v19
	v_mov_b32_e32 v40, v35
	v_lshlrev_b32_e32 v35, 16, v39
	v_add_f32_e32 v19, 1.0, v19
	v_rcp_f32_e32 v19, v19
	s_nop 0
	v_pk_mul_f32 v[18:19], v[18:19], v[40:41]
	s_nop 0
	v_mul_f32_e32 v38, v18, v19
	v_mul_f32_e32 v19, 0xbfb8aa3b, v35
	v_exp_f32_e32 v19, v19
	v_mul_f32_e32 v18, v20, v140
	v_mov_b32_e32 v20, v37
	v_add_f32_e32 v19, 1.0, v19
	v_rcp_f32_e32 v19, v19
	s_nop 0
	v_pk_mul_f32 v[18:19], v[18:19], v[34:35]
	s_nop 0
	v_mul_f32_e32 v34, v18, v19
	v_mul_f32_e32 v18, v21, v140
	v_and_b32_e32 v21, 0xffff0000, v39
	v_mul_f32_e32 v19, 0xbfb8aa3b, v21
	v_exp_f32_e32 v19, v19
	s_nop 0
	v_add_f32_e32 v19, 1.0, v19
	v_rcp_f32_e32 v19, v19
	s_nop 0
	v_pk_mul_f32 v[18:19], v[18:19], v[20:21]
	s_nop 0
	v_mul_f32_e32 v19, v18, v19
	v_cvt_pk_bf16_f32 v18, v42, v38
	v_cvt_pk_bf16_f32 v19, v34, v19
	global_store_dwordx2 v[134:135], v[18:19], off offset:384
	s_nop 0
	ds_read_b128 v[18:21], v242 offset:800
	s_waitcnt vmcnt(31)
	v_mov_b32_e32 v34, v228
	v_mov_b32_e32 v35, v229
	v_lshlrev_b32_e32 v39, 16, v34
	v_mul_f32_e32 v22, 0xbfb8aa3b, v39
	v_exp_f32_e32 v22, v22
	s_waitcnt lgkmcnt(0)
	v_mov_b32_e32 v38, v18
	v_add_f32_e32 v22, 1.0, v22
	v_rcp_f32_e32 v37, v22
	v_mul_f32_e32 v22, v23, v140
	v_pk_mul_f32 v[36:37], v[36:37], v[38:39]
	s_nop 0
	v_mul_f32_e32 v38, v36, v37
	v_and_b32_e32 v37, 0xffff0000, v34
	v_mul_f32_e32 v18, 0xbfb8aa3b, v37
	v_exp_f32_e32 v18, v18
	v_mov_b32_e32 v36, v19
	v_add_f32_e32 v18, 1.0, v18
	v_rcp_f32_e32 v23, v18
	s_nop 0
	v_pk_mul_f32 v[18:19], v[22:23], v[36:37]
	v_lshlrev_b32_e32 v23, 16, v35
	v_mul_f32_e32 v34, v18, v19
	v_mul_f32_e32 v19, 0xbfb8aa3b, v23
	v_exp_f32_e32 v19, v19
	v_mul_f32_e32 v18, v24, v140
	v_mov_b32_e32 v22, v20
	v_mul_f32_e32 v24, v26, v140
	v_add_f32_e32 v19, 1.0, v19
	v_rcp_f32_e32 v19, v19
	s_nop 0
	v_pk_mul_f32 v[18:19], v[18:19], v[22:23]
	v_and_b32_e32 v23, 0xffff0000, v35
	v_mul_f32_e32 v20, v18, v19
	v_mul_f32_e32 v19, 0xbfb8aa3b, v23
	v_exp_f32_e32 v19, v19
	v_mul_f32_e32 v18, v25, v140
	v_mov_b32_e32 v22, v21
	v_add_f32_e32 v19, 1.0, v19
	v_rcp_f32_e32 v19, v19
	s_nop 0
	v_pk_mul_f32 v[18:19], v[18:19], v[22:23]
	s_nop 0
	v_mul_f32_e32 v19, v18, v19
	v_cvt_pk_bf16_f32 v18, v38, v34
	v_cvt_pk_bf16_f32 v19, v20, v19
	global_store_dwordx2 v[134:135], v[18:19], off offset:400
	s_nop 0
	ds_read_b128 v[18:21], v242 offset:832
	s_waitcnt vmcnt(31)
; __device__ __forceinline__ unsigned cvt_pk_bf16(float lo, float hi) { unsigned r; asm volatile("v_cvt_pk_bf16_f32 %0, %1, %2" : "=v"(r) : "v"(lo), "v"(hi)); return r; }
; __device__ __forceinline__ float bf_lo(unsigned w) { return __uint_as_float(w << 16); }
; __device__ __forceinline__ float bf_hi(unsigned w) { return __uint_as_float(w & 0xffff0000u); }
; __device__ __forceinline__ float siluf_(float v) { return v * sigmoidf_(v); }
; __device__ __forceinline__ void gla_out(const Params& p, LAS unsigned char* lds, int l) {
;     ...
;             for (int dvb = 0; dvb < 8; ++dvb)
; #pragma unroll
;                 for (int rq = 0; rq < 4; ++rq) { const int dv = dvb * 32 + 8 * rq + 4 * hi; const u32x2 zz = *(const u32x2*)(zp + dv); const f32x4 g4 = *(const f32x4*)(gn + dv);
;                     const float y0 = o[dvb][rq * 4 + 0] * rs * g4[0] * siluf_(bf_lo(zz.x)), y1 = o[dvb][rq * 4 + 1] * rs * g4[1] * siluf_(bf_hi(zz.x));
;                     const float y2 = o[dvb][rq * 4 + 2] * rs * g4[2] * siluf_(bf_lo(zz.y)), y3 = o[dvb][rq * 4 + 3] * rs * g4[3] * siluf_(bf_hi(zz.y));
;                     u32x2 w; w.x = cvt_pk_bf16(y0, y1); w.y = cvt_pk_bf16(y2, y3); *(u32x2*)(zp + dv) = w; }
	v_mov_b32_e32 v22, v230
	v_mov_b32_e32 v23, v231
	v_lshlrev_b32_e32 v35, 16, v22
	v_mul_f32_e32 v25, 0xbfb8aa3b, v35
	v_exp_f32_e32 v25, v25
	s_waitcnt lgkmcnt(0)
	v_mov_b32_e32 v34, v18
	v_mov_b32_e32 v26, v19
	v_add_f32_e32 v25, 1.0, v25
	v_rcp_f32_e32 v25, v25
	s_nop 0
	v_pk_mul_f32 v[24:25], v[24:25], v[34:35]
	s_nop 0
	v_mul_f32_e32 v34, v24, v25
	v_mul_f32_e32 v24, v27, v140
	v_and_b32_e32 v27, 0xffff0000, v22
	v_mul_f32_e32 v18, 0xbfb8aa3b, v27
	v_exp_f32_e32 v18, v18
	v_mov_b32_e32 v22, v21
	v_add_f32_e32 v18, 1.0, v18
	v_rcp_f32_e32 v25, v18
	s_nop 0
	v_pk_mul_f32 v[18:19], v[24:25], v[26:27]
	v_lshlrev_b32_e32 v25, 16, v23
	v_mul_f32_e32 v26, v18, v19
	v_mul_f32_e32 v19, 0xbfb8aa3b, v25
	v_exp_f32_e32 v19, v19
	v_mul_f32_e32 v18, v28, v140
	v_mov_b32_e32 v24, v20
	v_and_b32_e32 v23, 0xffff0000, v23
	v_add_f32_e32 v19, 1.0, v19
	v_rcp_f32_e32 v19, v19
	s_nop 0
	v_pk_mul_f32 v[18:19], v[18:19], v[24:25]
	s_nop 0
	v_mul_f32_e32 v20, v18, v19
	v_mul_f32_e32 v19, 0xbfb8aa3b, v23
	v_exp_f32_e32 v19, v19
	v_mul_f32_e32 v18, v29, v140
	v_mul_f32_e32 v24, v30, v140
	v_add_f32_e32 v19, 1.0, v19
	v_rcp_f32_e32 v19, v19
	s_nop 0
	v_pk_mul_f32 v[18:19], v[18:19], v[22:23]
	s_nop 0
	v_mul_f32_e32 v19, v18, v19
	v_cvt_pk_bf16_f32 v18, v34, v26
	v_cvt_pk_bf16_f32 v19, v20, v19
	global_store_dwordx2 v[134:135], v[18:19], off offset:416
	s_nop 0
	ds_read_b128 v[18:21], v242 offset:864
	s_waitcnt vmcnt(31)
	v_mov_b32_e32 v22, v232
	v_mov_b32_e32 v23, v233
	v_lshlrev_b32_e32 v27, 16, v22
	v_mul_f32_e32 v25, 0xbfb8aa3b, v27
	v_exp_f32_e32 v25, v25
	s_waitcnt lgkmcnt(0)
	v_mov_b32_e32 v26, v18
	v_add_f32_e32 v25, 1.0, v25
	v_rcp_f32_e32 v25, v25
	s_nop 0
	v_pk_mul_f32 v[24:25], v[24:25], v[26:27]
	v_and_b32_e32 v27, 0xffff0000, v22
	v_mul_f32_e32 v18, 0xbfb8aa3b, v27
	v_exp_f32_e32 v18, v18
	v_mul_f32_e32 v28, v24, v25
	v_mul_f32_e32 v24, v31, v140
	v_mov_b32_e32 v26, v19
	v_add_f32_e32 v18, 1.0, v18
	v_rcp_f32_e32 v25, v18
	v_mov_b32_e32 v22, v21
	v_pk_mul_f32 v[18:19], v[24:25], v[26:27]
	v_lshlrev_b32_e32 v25, 16, v23
	v_mul_f32_e32 v26, v18, v19
	v_mul_f32_e32 v19, 0xbfb8aa3b, v25
	v_exp_f32_e32 v19, v19
	v_mul_f32_e32 v18, v32, v140
	v_mov_b32_e32 v24, v20
	v_and_b32_e32 v23, 0xffff0000, v23
	v_add_f32_e32 v19, 1.0, v19
	v_rcp_f32_e32 v19, v19
	s_nop 0
	v_pk_mul_f32 v[18:19], v[18:19], v[24:25]
	s_nop 0
	v_mul_f32_e32 v20, v18, v19
	v_mul_f32_e32 v19, 0xbfb8aa3b, v23
	v_exp_f32_e32 v19, v19
	v_mul_f32_e32 v18, v33, v140
	v_mul_f32_e32 v24, v2, v140
	v_add_f32_e32 v19, 1.0, v19
	v_rcp_f32_e32 v19, v19
	s_nop 0
	v_pk_mul_f32 v[18:19], v[18:19], v[22:23]
	s_nop 0
	v_mul_f32_e32 v19, v18, v19
	v_cvt_pk_bf16_f32 v18, v28, v26
	v_cvt_pk_bf16_f32 v19, v20, v19
	global_store_dwordx2 v[134:135], v[18:19], off offset:432
	s_nop 0
	ds_read_b128 v[18:21], v242 offset:896
	s_waitcnt vmcnt(31)
	v_mov_b32_e32 v22, v234
	v_mov_b32_e32 v23, v235
	v_lshlrev_b32_e32 v27, 16, v22
	v_mul_f32_e32 v2, 0xbfb8aa3b, v27
	v_exp_f32_e32 v2, v2
	s_waitcnt lgkmcnt(0)
	v_mov_b32_e32 v26, v18
	v_mov_b32_e32 v18, v20
	v_mul_f32_e32 v20, v6, v140
	v_add_f32_e32 v2, 1.0, v2
	v_rcp_f32_e32 v25, v2
	v_mul_f32_e32 v2, v3, v140
	v_pk_mul_f32 v[24:25], v[24:25], v[26:27]
	s_nop 0
	v_mul_f32_e32 v26, v24, v25
	v_and_b32_e32 v25, 0xffff0000, v22
	v_mul_f32_e32 v3, 0xbfb8aa3b, v25
	v_exp_f32_e32 v3, v3
	v_mov_b32_e32 v24, v19
	v_lshlrev_b32_e32 v19, 16, v23
	v_add_f32_e32 v3, 1.0, v3
	v_rcp_f32_e32 v3, v3
	s_nop 0
	v_pk_mul_f32 v[2:3], v[2:3], v[24:25]
	s_nop 0
	v_mul_f32_e32 v22, v2, v3
	v_mul_f32_e32 v3, 0xbfb8aa3b, v19
	v_exp_f32_e32 v3, v3
	v_mul_f32_e32 v2, v4, v140
	v_mov_b32_e32 v4, v21
	v_add_f32_e32 v3, 1.0, v3
	v_rcp_f32_e32 v3, v3
	s_nop 0
	v_pk_mul_f32 v[2:3], v[2:3], v[18:19]
	s_nop 0
	v_mul_f32_e32 v18, v2, v3
	v_mul_f32_e32 v2, v5, v140
	v_and_b32_e32 v5, 0xffff0000, v23
	v_mul_f32_e32 v3, 0xbfb8aa3b, v5
	v_exp_f32_e32 v3, v3
	s_nop 0
	v_add_f32_e32 v3, 1.0, v3
	v_rcp_f32_e32 v3, v3
	s_nop 0
	v_pk_mul_f32 v[2:3], v[2:3], v[4:5]
	s_nop 0
	v_mul_f32_e32 v3, v2, v3
	v_cvt_pk_bf16_f32 v2, v26, v22
	v_cvt_pk_bf16_f32 v3, v18, v3
	global_store_dwordx2 v[134:135], v[2:3], off offset:448
	s_nop 0
	ds_read_b128 v[2:5], v242 offset:928
	s_waitcnt vmcnt(31)
; __device__ __forceinline__ unsigned cvt_pk_bf16(float lo, float hi) { unsigned r; asm volatile("v_cvt_pk_bf16_f32 %0, %1, %2" : "=v"(r) : "v"(lo), "v"(hi)); return r; }
; __device__ __forceinline__ float bf_lo(unsigned w) { return __uint_as_float(w << 16); }
; __device__ __forceinline__ float bf_hi(unsigned w) { return __uint_as_float(w & 0xffff0000u); }
; __device__ __forceinline__ float siluf_(float v) { return v * sigmoidf_(v); }
; __device__ __forceinline__ void gla_out(const Params& p, LAS unsigned char* lds, int l) {
;     ...
;             for (int dvb = 0; dvb < 8; ++dvb)
; #pragma unroll
;                 for (int rq = 0; rq < 4; ++rq) { const int dv = dvb * 32 + 8 * rq + 4 * hi; const u32x2 zz = *(const u32x2*)(zp + dv); const f32x4 g4 = *(const f32x4*)(gn + dv);
;                     const float y0 = o[dvb][rq * 4 + 0] * rs * g4[0] * siluf_(bf_lo(zz.x)), y1 = o[dvb][rq * 4 + 1] * rs * g4[1] * siluf_(bf_hi(zz.x));
;                     const float y2 = o[dvb][rq * 4 + 2] * rs * g4[2] * siluf_(bf_lo(zz.y)), y3 = o[dvb][rq * 4 + 3] * rs * g4[3] * siluf_(bf_hi(zz.y));
;                     u32x2 w; w.x = cvt_pk_bf16(y0, y1); w.y = cvt_pk_bf16(y2, y3); *(u32x2*)(zp + dv) = w; }
;         }
;         __syncthreads();
	v_mov_b32_e32 v18, v236
	v_mov_b32_e32 v19, v237
	v_lshlrev_b32_e32 v23, 16, v18
	v_mul_f32_e32 v6, 0xbfb8aa3b, v23
	v_exp_f32_e32 v6, v6
	s_waitcnt lgkmcnt(0)
	v_mov_b32_e32 v22, v2
	v_add_f32_e32 v6, 1.0, v6
	v_rcp_f32_e32 v21, v6
	v_mul_f32_e32 v6, v7, v140
	v_pk_mul_f32 v[20:21], v[20:21], v[22:23]
	s_nop 0
	v_mul_f32_e32 v22, v20, v21
	v_and_b32_e32 v21, 0xffff0000, v18
	v_mul_f32_e32 v2, 0xbfb8aa3b, v21
	v_exp_f32_e32 v2, v2
	v_mov_b32_e32 v20, v3
	v_add_f32_e32 v2, 1.0, v2
	v_rcp_f32_e32 v7, v2
	s_nop 0
	v_pk_mul_f32 v[2:3], v[6:7], v[20:21]
	v_lshlrev_b32_e32 v7, 16, v19
	v_mul_f32_e32 v18, v2, v3
	v_mul_f32_e32 v3, 0xbfb8aa3b, v7
	v_exp_f32_e32 v3, v3
	v_mul_f32_e32 v2, v8, v140
	v_mov_b32_e32 v6, v4
	v_mul_f32_e32 v8, v10, v140
	v_add_f32_e32 v3, 1.0, v3
	v_rcp_f32_e32 v3, v3
	s_nop 0
	v_pk_mul_f32 v[2:3], v[2:3], v[6:7]
	v_and_b32_e32 v7, 0xffff0000, v19
	v_mul_f32_e32 v4, v2, v3
	v_mul_f32_e32 v3, 0xbfb8aa3b, v7
	v_exp_f32_e32 v3, v3
	v_mul_f32_e32 v2, v9, v140
	v_mov_b32_e32 v6, v5
	v_add_f32_e32 v3, 1.0, v3
	v_rcp_f32_e32 v3, v3
	s_nop 0
	v_pk_mul_f32 v[2:3], v[2:3], v[6:7]
	s_nop 0
	v_mul_f32_e32 v3, v2, v3
	v_cvt_pk_bf16_f32 v2, v22, v18
	v_cvt_pk_bf16_f32 v3, v4, v3
	global_store_dwordx2 v[134:135], v[2:3], off offset:464
	s_nop 0
	ds_read_b128 v[2:5], v242 offset:960
	s_waitcnt vmcnt(31)
	v_mov_b32_e32 v6, v238
	v_mov_b32_e32 v7, v239
	v_lshlrev_b32_e32 v19, 16, v6
	v_mul_f32_e32 v9, 0xbfb8aa3b, v19
	v_exp_f32_e32 v9, v9
	s_waitcnt lgkmcnt(0)
	v_mov_b32_e32 v18, v2
	v_mov_b32_e32 v10, v3
	v_add_f32_e32 v9, 1.0, v9
	v_rcp_f32_e32 v9, v9
	s_nop 0
	v_pk_mul_f32 v[8:9], v[8:9], v[18:19]
	s_nop 0
	v_mul_f32_e32 v18, v8, v9
	v_mul_f32_e32 v8, v11, v140
	v_and_b32_e32 v11, 0xffff0000, v6
	v_mul_f32_e32 v2, 0xbfb8aa3b, v11
	v_exp_f32_e32 v2, v2
	v_mov_b32_e32 v6, v5
	v_add_f32_e32 v2, 1.0, v2
	v_rcp_f32_e32 v9, v2
	s_nop 0
	v_pk_mul_f32 v[2:3], v[8:9], v[10:11]
	v_lshlrev_b32_e32 v9, 16, v7
	v_mul_f32_e32 v10, v2, v3
	v_mul_f32_e32 v3, 0xbfb8aa3b, v9
	v_exp_f32_e32 v3, v3
	v_mul_f32_e32 v2, v12, v140
	v_mov_b32_e32 v8, v4
	v_and_b32_e32 v7, 0xffff0000, v7
	v_add_f32_e32 v3, 1.0, v3
	v_rcp_f32_e32 v3, v3
	s_nop 0
	v_pk_mul_f32 v[2:3], v[2:3], v[8:9]
	s_nop 0
	v_mul_f32_e32 v4, v2, v3
	v_mul_f32_e32 v3, 0xbfb8aa3b, v7
	v_exp_f32_e32 v3, v3
	v_mul_f32_e32 v2, v13, v140
	v_mul_f32_e32 v8, v14, v140
	v_add_f32_e32 v3, 1.0, v3
	v_rcp_f32_e32 v3, v3
	s_nop 0
	v_pk_mul_f32 v[2:3], v[2:3], v[6:7]
	s_nop 0
	v_mul_f32_e32 v3, v2, v3
	v_cvt_pk_bf16_f32 v2, v18, v10
	v_cvt_pk_bf16_f32 v3, v4, v3
	global_store_dwordx2 v[134:135], v[2:3], off offset:480
	s_nop 0
	ds_read_b128 v[2:5], v242 offset:992
	s_waitcnt vmcnt(31)
	v_mov_b32_e32 v6, v240
	v_mov_b32_e32 v7, v241
	v_lshlrev_b32_e32 v11, 16, v6
	v_mul_f32_e32 v9, 0xbfb8aa3b, v11
	v_exp_f32_e32 v9, v9
	s_waitcnt lgkmcnt(0)
	v_mov_b32_e32 v10, v2
	v_add_f32_e32 v9, 1.0, v9
	v_rcp_f32_e32 v9, v9
	s_nop 0
	v_pk_mul_f32 v[8:9], v[8:9], v[10:11]
	v_and_b32_e32 v11, 0xffff0000, v6
	v_mul_f32_e32 v2, 0xbfb8aa3b, v11
	v_exp_f32_e32 v2, v2
	v_mul_f32_e32 v12, v8, v9
	v_mul_f32_e32 v8, v15, v140
	v_mov_b32_e32 v10, v3
	v_add_f32_e32 v2, 1.0, v2
	v_rcp_f32_e32 v9, v2
	v_mov_b32_e32 v6, v5
	v_pk_mul_f32 v[2:3], v[8:9], v[10:11]
	v_lshlrev_b32_e32 v9, 16, v7
	v_mul_f32_e32 v10, v2, v3
	v_mul_f32_e32 v3, 0xbfb8aa3b, v9
	v_exp_f32_e32 v3, v3
	v_mul_f32_e32 v2, v16, v140
	v_mov_b32_e32 v8, v4
	v_and_b32_e32 v7, 0xffff0000, v7
	v_add_f32_e32 v3, 1.0, v3
	v_rcp_f32_e32 v3, v3
	s_nop 0
	v_pk_mul_f32 v[2:3], v[2:3], v[8:9]
	s_nop 0
	v_mul_f32_e32 v4, v2, v3
	v_mul_f32_e32 v3, 0xbfb8aa3b, v7
	v_exp_f32_e32 v3, v3
	v_mul_f32_e32 v2, v17, v140
	v_add_f32_e32 v3, 1.0, v3
	v_rcp_f32_e32 v3, v3
	s_nop 0
	v_pk_mul_f32 v[2:3], v[2:3], v[6:7]
	s_nop 0
	v_mul_f32_e32 v3, v2, v3
	v_cvt_pk_bf16_f32 v2, v12, v10
	v_cvt_pk_bf16_f32 v3, v4, v3
	global_store_dwordx2 v[134:135], v[2:3], off offset:496
	s_barrier
	s_add_i32 s34, s0, s34
	s_cmpk_gt_i32 s34, 0xff
	s_cbranch_scc1 .LBB0_366
